# v6 + G epilogue counted vmcnt waits relaxed by one (stores were not counted by the compiler)
# baseline (speedup 1.0000x reference)
; #define GAS __attribute__((address_space(1)))
; __device__ __forceinline__ u32x4 pack8(f32x4 a, f32x4 b) { u32x4 w; w.x = cvt_pk_bf16(a[0], a[1]); w.y = cvt_pk_bf16(a[2], a[3]); w.z = cvt_pk_bf16(b[0], b[1]); w.w = cvt_pk_bf16(b[2], b[3]); return w; }
; __device__ __forceinline__ float bf_lo(unsigned w) { return __uint_as_float(w << 16); }
; __device__ __forceinline__ float bf_hi(unsigned w) { return __uint_as_float(w & 0xffff0000u); }
; __device__ __forceinline__ void st_rows_f32(float* Y, int row, int col, int fr, f32x4 y0, f32x4 y1) {
;     const bool lo8 = fr < 8; const f32x4 snd = lo8 ? y1 : y0, rcv = dpp_ror8(snd);
;     const size_t a1 = lo8 ? (size_t)row * DM + col : (size_t)(row - 8) * DM + col + 4, a2 = lo8 ? (size_t)(row + 8) * DM + col : (size_t)row * DM + col + 4;
;     __builtin_nontemporal_store(lo8 ? y0 : rcv, (GAS f32x4*)(uintptr_t)(Y + a1)); __builtin_nontemporal_store(lo8 ? rcv : y1, (GAS f32x4*)(uintptr_t)(Y + a2));
; }
;     __device__ __forceinline__ void operator()(EP_ARGS) const {
;     ...
;             PLE_LD(0, 0);
; #pragma unroll
;             for (int k = 0; k < 8; ++k) { const int ai = k >> 2, m = k & 3;
;                 if (k < 7) PLE_LD(k + 1, (k + 1) & 1);
;                 __builtin_amdgcn_sched_barrier(0);
;                 { const int row = EP_ROW(ai, m); float mu, rstd; ln_unpack(tq[k & 1], mu, rstd); const size_t o = (size_t)row * DM + col;
;                     const u32x4 w_ = iw[k & 1], pw = pq[k & 1]; const f32x4 r0 = {bf_lo(w_.x), bf_hi(w_.x), bf_lo(w_.y), bf_hi(w_.y)}, r1 = {bf_lo(w_.z), bf_hi(w_.z), bf_lo(w_.w), bf_hi(w_.w)};
;                     const f32x4 x0 = (r0 - mu) * rstd * g0 + b0, x1 = (r1 - mu) * rstd * g1 + b1;
;                     const f32x4 t0 = (acc[ai][bj][m][0] - c0 * mu) * rstd + w0, t1 = (acc[ai][bj][m][1] - c1 * mu) * rstd + w1;
;                     const f32x4 p0 = {bf_lo(pw.x), bf_hi(pw.x), bf_lo(pw.y), bf_hi(pw.y)}, p1 = {bf_lo(pw.z), bf_hi(pw.z), bf_lo(pw.w), bf_hi(pw.w)};
;                     f32x4 y0, y1;
; #pragma unroll
;                     for (int j = 0; j < 4; ++j) { y0[j] = x0[j] + sigmoidf_(t0[j]) * p0[j]; y1[j] = x1[j] + sigmoidf_(t1[j]) * p1[j]; }
;                     if (Xf) st_rows_f32(Xf, row, col, fr, y0, y1); else *(GAS u32x4*)(uintptr_t)(Oh + o) = pack8(y0, y1); }
.LBB0_1793:
	v_or_b32_e32 v204, 48, v178
	v_ashrrev_i32_e32 v205, 31, v204
	v_lshlrev_b64 v[160:161], 11, v[204:205]
	v_lshl_add_u64 v[212:213], v[160:161], 0, v[176:177]
	v_lshlrev_b64 v[144:145], 1, v[212:213]
	v_lshl_add_u64 v[164:165], s[36:37], 0, v[144:145]
	v_lshl_add_u64 v[166:167], s[30:31], 0, v[144:145]
	global_load_dwordx2 v[216:217], v[182:183], off offset:384
	global_load_dwordx4 v[148:151], v[164:165], off
	global_load_dwordx4 v[144:147], v[166:167], off
	s_waitcnt vmcnt(6)
	v_cvt_f32_u32_e32 v190, v214
	v_cvt_f32_i32_e32 v191, v215
	s_mov_b32 s12, 0x35000000
	s_mov_b32 s13, 0x33000000
	s_waitcnt vmcnt(5)
	v_lshlrev_b32_e32 v179, 16, v156
	v_pk_mul_f32 v[190:191], v[190:191], s[12:13]
	v_and_b32_e32 v202, 0xffff0000, v156
	v_fma_f32 v156, -v191, v191, v190
	v_max_f32_e32 v156, 0, v156
	v_add_f32_e32 v156, 0x3727c5ac, v156
	v_rsq_f32_e32 v156, v156
	v_fma_f32 v136, -v88, v191, v136
	v_fma_f32 v141, -v97, v191, v141
	v_fma_f32 v140, -v96, v191, v140
	v_fma_f32 v136, v136, v156, v92
	v_mul_f32_e32 v136, 0xbfb8aa3b, v136
	v_fma_f32 v141, v141, v156, v101
	v_exp_f32_e32 v136, v136
	v_mul_f32_e32 v141, 0xbfb8aa3b, v141
	v_exp_f32_e32 v141, v141
	v_fma_f32 v140, v140, v156, v100
	v_mul_f32_e32 v140, 0xbfb8aa3b, v140
	v_exp_f32_e32 v140, v140
	v_add_f32_e32 v136, 1.0, v136
	v_rcp_f32_e32 v222, v136
	v_add_f32_e32 v136, 1.0, v141
	v_fma_f32 v138, -v90, v191, v138
	v_rcp_f32_e32 v141, v136
	v_fma_f32 v136, -v89, v191, v137
	v_fma_f32 v138, v138, v156, v94
	v_fma_f32 v143, -v99, v191, v143
	v_fma_f32 v136, v136, v156, v93
	v_mul_f32_e32 v138, 0xbfb8aa3b, v138
	v_fma_f32 v143, v143, v156, v103
	v_add_f32_e32 v140, 1.0, v140
	v_mul_f32_e32 v136, 0xbfb8aa3b, v136
	v_exp_f32_e32 v138, v138
	v_mul_f32_e32 v143, 0xbfb8aa3b, v143
	v_rcp_f32_e32 v140, v140
	s_waitcnt vmcnt(4)
	v_lshlrev_b32_e32 v240, 16, v152
	v_and_b32_e32 v241, 0xffff0000, v152
	v_exp_f32_e32 v152, v136
	v_fma_f32 v142, -v98, v191, v142
	v_exp_f32_e32 v143, v143
	v_lshlrev_b32_e32 v190, 16, v157
	v_and_b32_e32 v157, 0xffff0000, v157
	v_sub_f32_e32 v203, v202, v191
	v_sub_f32_e32 v202, v179, v191
	v_fma_f32 v142, v142, v156, v102
	v_pk_mul_f32 v[202:203], v[202:203], v[156:157] op_sel_hi:[1,0]
	v_mul_f32_e32 v142, 0xbfb8aa3b, v142
	v_pk_fma_f32 v[136:137], v[120:121], v[202:203], v[124:125]
	v_exp_f32_e32 v142, v142
	v_add_f32_e32 v138, 1.0, v138
	v_pk_fma_f32 v[136:137], v[140:141], v[240:241], v[136:137]
	v_add_f32_e32 v140, 1.0, v152
	v_rcp_f32_e32 v152, v138
	v_add_f32_e32 v138, 1.0, v143
	v_rcp_f32_e32 v143, v138
	v_fma_f32 v138, -v91, v191, v139
	v_fma_f32 v138, v138, v156, v95
	v_add_f32_e32 v142, 1.0, v142
	v_mul_f32_e32 v138, 0xbfb8aa3b, v138
	v_rcp_f32_e32 v223, v140
	v_lshlrev_b32_e32 v140, 16, v154
	v_and_b32_e32 v141, 0xffff0000, v154
	v_rcp_f32_e32 v142, v142
	v_exp_f32_e32 v154, v138
	v_lshlrev_b32_e32 v218, 16, v158
	v_and_b32_e32 v219, 0xffff0000, v158
	v_lshlrev_b32_e32 v214, 16, v159
	v_and_b32_e32 v215, 0xffff0000, v159
	v_sub_f32_e32 v159, v157, v191
	v_sub_f32_e32 v158, v190, v191
	v_pk_mul_f32 v[158:159], v[158:159], v[156:157] op_sel_hi:[1,0]
	v_lshlrev_b32_e32 v138, 16, v153
	v_pk_fma_f32 v[158:159], v[122:123], v[158:159], v[126:127]
	v_and_b32_e32 v139, 0xffff0000, v153
	v_pk_fma_f32 v[138:139], v[142:143], v[138:139], v[158:159]
	v_add_f32_e32 v142, 1.0, v154
	v_rcp_f32_e32 v153, v142
	v_sub_f32_e32 v215, v215, v191
	v_sub_f32_e32 v214, v214, v191
	v_sub_f32_e32 v219, v219, v191
	v_sub_f32_e32 v218, v218, v191
	v_pk_mul_f32 v[218:219], v[218:219], v[156:157] op_sel_hi:[1,0]
	v_pk_mul_f32 v[214:215], v[214:215], v[156:157] op_sel_hi:[1,0]
	v_lshlrev_b32_e32 v142, 16, v155
	v_pk_fma_f32 v[202:203], v[110:111], v[214:215], v[114:115]
	v_pk_fma_f32 v[214:215], v[108:109], v[218:219], v[112:113]
	v_and_b32_e32 v143, 0xffff0000, v155
	v_pk_fma_f32 v[140:141], v[222:223], v[140:141], v[214:215]
	s_and_b64 vcc, exec, s[46:47]
	v_pk_fma_f32 v[142:143], v[152:153], v[142:143], v[202:203]
	s_cbranch_vccnz .LBB0_1896
	v_cndmask_b32_e64 v155, v139, v143, s[40:41]
	v_cndmask_b32_e64 v154, v138, v142, s[40:41]
	v_cndmask_b32_e64 v153, v137, v141, s[40:41]
	v_cndmask_b32_e64 v152, v136, v140, s[40:41]
	s_nop 1
	v_mov_b32_dpp v152, v152 row_ror:8 row_mask:0xf bank_mask:0xf
	s_nop 1
	v_mov_b32_dpp v153, v153 row_ror:8 row_mask:0xf bank_mask:0xf
	s_nop 1
	v_mov_b32_dpp v154, v154 row_ror:8 row_mask:0xf bank_mask:0xf
	s_nop 1
	v_mov_b32_dpp v155, v155 row_ror:8 row_mask:0xf bank_mask:0xf
	s_and_saveexec_b64 s[12:13], s[42:43]
	s_xor_b64 s[12:13], exec, s[12:13]
	v_mov_b64_e32 v[158:159], v[142:143]
	v_lshl_add_u64 v[202:203], v[168:169], 0, v[206:207]
	v_mov_b64_e32 v[156:157], v[140:141]
	s_andn2_saveexec_b64 s[12:13], s[12:13]
	v_or_b32_e32 v156, 40, v178
	v_ashrrev_i32_e32 v157, 31, v156
	v_lshlrev_b64 v[156:157], 11, v[156:157]
	v_lshl_add_u64 v[202:203], v[156:157], 0, v[176:177]
	v_mov_b64_e32 v[158:159], v[154:155]
	v_mov_b64_e32 v[156:157], v[152:153]
	v_mov_b64_e32 v[154:155], v[138:139]
	v_mov_b64_e32 v[152:153], v[136:137]
	s_or_b64 exec, exec, s[12:13]
	v_lshl_add_u64 v[190:191], v[180:181], 0, v[206:207]
	s_mov_b64 s[12:13], 0xc000
	v_lshl_add_u64 v[190:191], v[190:191], 0, s[12:13]
	v_cndmask_b32_e64 v191, v191, v211, s[40:41]
	v_cndmask_b32_e64 v190, v190, v210, s[40:41]
	v_lshl_add_u64 v[190:191], v[190:191], 2, s[4:5]
	global_store_dwordx4 v[190:191], v[152:155], off nt
	s_nop 1
	v_lshl_add_u64 v[152:153], v[202:203], 2, s[4:5]
	global_store_dwordx4 v[152:153], v[156:159], off nt
	v_lshlrev_b64 v[152:153], 12, v[208:209]
	s_nop 0
	v_lshl_add_u64 v[156:157], s[6:7], 0, v[152:153]
	s_branch .LBB0_1800

; #define GAS __attribute__((address_space(1)))
; __device__ __forceinline__ u32x4 pack8(f32x4 a, f32x4 b) { u32x4 w; w.x = cvt_pk_bf16(a[0], a[1]); w.y = cvt_pk_bf16(a[2], a[3]); w.z = cvt_pk_bf16(b[0], b[1]); w.w = cvt_pk_bf16(b[2], b[3]); return w; }
; __device__ __forceinline__ float bf_lo(unsigned w) { return __uint_as_float(w << 16); }
; __device__ __forceinline__ float bf_hi(unsigned w) { return __uint_as_float(w & 0xffff0000u); }
; __device__ __forceinline__ void st_rows_f32(float* Y, int row, int col, int fr, f32x4 y0, f32x4 y1) {
;     const bool lo8 = fr < 8; const f32x4 snd = lo8 ? y1 : y0, rcv = dpp_ror8(snd);
;     const size_t a1 = lo8 ? (size_t)row * DM + col : (size_t)(row - 8) * DM + col + 4, a2 = lo8 ? (size_t)(row + 8) * DM + col : (size_t)row * DM + col + 4;
;     __builtin_nontemporal_store(lo8 ? y0 : rcv, (GAS f32x4*)(uintptr_t)(Y + a1)); __builtin_nontemporal_store(lo8 ? rcv : y1, (GAS f32x4*)(uintptr_t)(Y + a2));
; }
;     __device__ __forceinline__ void operator()(EP_ARGS) const {
;     ...
;             PLE_LD(0, 0);
; #pragma unroll
;             for (int k = 0; k < 8; ++k) { const int ai = k >> 2, m = k & 3;
;                 if (k < 7) PLE_LD(k + 1, (k + 1) & 1);
;                 __builtin_amdgcn_sched_barrier(0);
;                 { const int row = EP_ROW(ai, m); float mu, rstd; ln_unpack(tq[k & 1], mu, rstd); const size_t o = (size_t)row * DM + col;
;                     const u32x4 w_ = iw[k & 1], pw = pq[k & 1]; const f32x4 r0 = {bf_lo(w_.x), bf_hi(w_.x), bf_lo(w_.y), bf_hi(w_.y)}, r1 = {bf_lo(w_.z), bf_hi(w_.z), bf_lo(w_.w), bf_hi(w_.w)};
;                     const f32x4 x0 = (r0 - mu) * rstd * g0 + b0, x1 = (r1 - mu) * rstd * g1 + b1;
;                     const f32x4 t0 = (acc[ai][bj][m][0] - c0 * mu) * rstd + w0, t1 = (acc[ai][bj][m][1] - c1 * mu) * rstd + w1;
;                     const f32x4 p0 = {bf_lo(pw.x), bf_hi(pw.x), bf_lo(pw.y), bf_hi(pw.y)}, p1 = {bf_lo(pw.z), bf_hi(pw.z), bf_lo(pw.w), bf_hi(pw.w)};
;                     f32x4 y0, y1;
; #pragma unroll
;                     for (int j = 0; j < 4; ++j) { y0[j] = x0[j] + sigmoidf_(t0[j]) * p0[j]; y1[j] = x1[j] + sigmoidf_(t1[j]) * p1[j]; }
;                     if (Xf) st_rows_f32(Xf, row, col, fr, y0, y1); else *(GAS u32x4*)(uintptr_t)(Oh + o) = pack8(y0, y1); }
.LBB0_1800:
	v_add_u32_e32 v152, 0x80, v178
	v_ashrrev_i32_e32 v153, 31, v152
	v_lshlrev_b64 v[154:155], 11, v[152:153]
	v_lshl_add_u64 v[210:211], v[154:155], 0, v[176:177]
	v_lshlrev_b64 v[136:137], 1, v[210:211]
	v_lshl_add_u64 v[158:159], s[36:37], 0, v[136:137]
	v_lshl_add_u64 v[202:203], s[30:31], 0, v[136:137]
	global_load_dwordx2 v[214:215], v[182:183], off offset:1024
	global_load_dwordx4 v[140:143], v[158:159], off
	global_load_dwordx4 v[136:139], v[202:203], off
	s_waitcnt vmcnt(6)
	v_cvt_f32_u32_e32 v190, v216
	v_cvt_f32_i32_e32 v191, v217
	s_mov_b32 s12, 0x35000000
	s_mov_b32 s13, 0x33000000
	s_waitcnt vmcnt(5)
	v_lshlrev_b32_e32 v179, 16, v148
	v_pk_mul_f32 v[190:191], v[190:191], s[12:13]
	v_and_b32_e32 v208, 0xffff0000, v148
	v_fma_f32 v148, -v191, v191, v190
	v_max_f32_e32 v148, 0, v148
	v_add_f32_e32 v148, 0x3727c5ac, v148
	v_rsq_f32_e32 v148, v148
	v_fma_f32 v128, -v88, v191, v128
	v_fma_f32 v133, -v97, v191, v133
	v_fma_f32 v132, -v96, v191, v132
	v_fma_f32 v128, v128, v148, v92
	v_mul_f32_e32 v128, 0xbfb8aa3b, v128
	v_fma_f32 v133, v133, v148, v101
	v_exp_f32_e32 v128, v128
	v_mul_f32_e32 v133, 0xbfb8aa3b, v133
	v_exp_f32_e32 v133, v133
	v_fma_f32 v132, v132, v148, v100
	v_mul_f32_e32 v132, 0xbfb8aa3b, v132
	v_exp_f32_e32 v132, v132
	v_add_f32_e32 v128, 1.0, v128
	v_rcp_f32_e32 v222, v128
	v_add_f32_e32 v128, 1.0, v133
	v_fma_f32 v130, -v90, v191, v130
	v_rcp_f32_e32 v133, v128
	v_fma_f32 v128, -v89, v191, v129
	v_fma_f32 v130, v130, v148, v94
	v_fma_f32 v135, -v99, v191, v135
	v_fma_f32 v128, v128, v148, v93
	v_mul_f32_e32 v130, 0xbfb8aa3b, v130
	v_fma_f32 v135, v135, v148, v103
	v_add_f32_e32 v132, 1.0, v132
	v_mul_f32_e32 v128, 0xbfb8aa3b, v128
	v_exp_f32_e32 v130, v130
	v_mul_f32_e32 v135, 0xbfb8aa3b, v135
	v_rcp_f32_e32 v132, v132
	s_waitcnt vmcnt(4)
	v_lshlrev_b32_e32 v240, 16, v144
	v_and_b32_e32 v241, 0xffff0000, v144
	v_exp_f32_e32 v144, v128
	v_fma_f32 v134, -v98, v191, v134
	v_exp_f32_e32 v135, v135
	v_lshlrev_b32_e32 v190, 16, v149
	v_and_b32_e32 v149, 0xffff0000, v149
	v_sub_f32_e32 v209, v208, v191
	v_sub_f32_e32 v208, v179, v191
	v_fma_f32 v134, v134, v148, v102
	v_pk_mul_f32 v[208:209], v[208:209], v[148:149] op_sel_hi:[1,0]
	v_mul_f32_e32 v134, 0xbfb8aa3b, v134
	v_pk_fma_f32 v[128:129], v[120:121], v[208:209], v[124:125]
	v_exp_f32_e32 v134, v134
	v_add_f32_e32 v130, 1.0, v130
	v_pk_fma_f32 v[128:129], v[132:133], v[240:241], v[128:129]
	v_add_f32_e32 v132, 1.0, v144
	v_rcp_f32_e32 v144, v130
	v_add_f32_e32 v130, 1.0, v135
	v_rcp_f32_e32 v135, v130
	v_fma_f32 v130, -v91, v191, v131
	v_fma_f32 v130, v130, v148, v95
	v_add_f32_e32 v134, 1.0, v134
	v_mul_f32_e32 v130, 0xbfb8aa3b, v130
	v_rcp_f32_e32 v223, v132
	v_lshlrev_b32_e32 v132, 16, v146
	v_and_b32_e32 v133, 0xffff0000, v146
	v_rcp_f32_e32 v134, v134
	v_exp_f32_e32 v146, v130
	v_lshlrev_b32_e32 v218, 16, v150
	v_and_b32_e32 v219, 0xffff0000, v150
	v_lshlrev_b32_e32 v216, 16, v151
	v_and_b32_e32 v217, 0xffff0000, v151
	v_sub_f32_e32 v151, v149, v191
	v_sub_f32_e32 v150, v190, v191
	v_pk_mul_f32 v[150:151], v[150:151], v[148:149] op_sel_hi:[1,0]
	v_lshlrev_b32_e32 v130, 16, v145
	v_pk_fma_f32 v[150:151], v[122:123], v[150:151], v[126:127]
	v_and_b32_e32 v131, 0xffff0000, v145
	v_pk_fma_f32 v[130:131], v[134:135], v[130:131], v[150:151]
	v_add_f32_e32 v134, 1.0, v146
	v_rcp_f32_e32 v145, v134
	v_sub_f32_e32 v217, v217, v191
	v_sub_f32_e32 v216, v216, v191
	v_sub_f32_e32 v219, v219, v191
	v_sub_f32_e32 v218, v218, v191
	v_pk_mul_f32 v[218:219], v[218:219], v[148:149] op_sel_hi:[1,0]
	v_pk_mul_f32 v[216:217], v[216:217], v[148:149] op_sel_hi:[1,0]
	v_lshlrev_b32_e32 v134, 16, v147
	v_pk_fma_f32 v[208:209], v[110:111], v[216:217], v[114:115]
	v_pk_fma_f32 v[216:217], v[108:109], v[218:219], v[112:113]
	v_and_b32_e32 v135, 0xffff0000, v147
	v_pk_fma_f32 v[132:133], v[222:223], v[132:133], v[216:217]
	s_and_b64 vcc, exec, s[46:47]
	v_pk_fma_f32 v[134:135], v[144:145], v[134:135], v[208:209]
	s_cbranch_vccnz .LBB0_1897
	v_cndmask_b32_e64 v147, v131, v135, s[40:41]
	v_cndmask_b32_e64 v146, v130, v134, s[40:41]
	v_cndmask_b32_e64 v145, v129, v133, s[40:41]
	v_cndmask_b32_e64 v144, v128, v132, s[40:41]
	s_nop 1
	v_mov_b32_dpp v144, v144 row_ror:8 row_mask:0xf bank_mask:0xf
	s_nop 1
	v_mov_b32_dpp v145, v145 row_ror:8 row_mask:0xf bank_mask:0xf
	s_nop 1
	v_mov_b32_dpp v146, v146 row_ror:8 row_mask:0xf bank_mask:0xf
	s_nop 1
	v_mov_b32_dpp v147, v147 row_ror:8 row_mask:0xf bank_mask:0xf
	s_and_saveexec_b64 s[12:13], s[42:43]
	s_xor_b64 s[12:13], exec, s[12:13]
	v_mov_b64_e32 v[150:151], v[134:135]
	v_lshl_add_u64 v[208:209], v[160:161], 0, v[206:207]
	v_mov_b64_e32 v[148:149], v[132:133]
	s_andn2_saveexec_b64 s[12:13], s[12:13]
	v_or_b32_e32 v148, 56, v178
	v_ashrrev_i32_e32 v149, 31, v148
	v_lshlrev_b64 v[148:149], 11, v[148:149]
	v_lshl_add_u64 v[208:209], v[148:149], 0, v[176:177]
	v_mov_b64_e32 v[150:151], v[146:147]
	v_mov_b64_e32 v[148:149], v[144:145]
	v_mov_b64_e32 v[146:147], v[130:131]
	v_mov_b64_e32 v[144:145], v[128:129]
	s_or_b64 exec, exec, s[12:13]
	v_lshl_add_u64 v[190:191], v[180:181], 0, v[206:207]
	s_mov_b64 s[12:13], 0x14000
	v_lshl_add_u64 v[190:191], v[190:191], 0, s[12:13]
	v_cndmask_b32_e64 v191, v191, v213, s[40:41]
	v_cndmask_b32_e64 v190, v190, v212, s[40:41]
	v_lshl_add_u64 v[190:191], v[190:191], 2, s[4:5]
	global_store_dwordx4 v[190:191], v[144:147], off nt
	s_nop 1
	v_lshl_add_u64 v[144:145], v[208:209], 2, s[4:5]
	global_store_dwordx4 v[144:145], v[148:151], off nt
	v_lshlrev_b64 v[144:145], 12, v[204:205]
	s_nop 0
	v_lshl_add_u64 v[148:149], s[6:7], 0, v[144:145]
	s_branch .LBB0_1807

; #define GAS __attribute__((address_space(1)))
; __device__ __forceinline__ u32x4 pack8(f32x4 a, f32x4 b) { u32x4 w; w.x = cvt_pk_bf16(a[0], a[1]); w.y = cvt_pk_bf16(a[2], a[3]); w.z = cvt_pk_bf16(b[0], b[1]); w.w = cvt_pk_bf16(b[2], b[3]); return w; }
; __device__ __forceinline__ float bf_lo(unsigned w) { return __uint_as_float(w << 16); }
; __device__ __forceinline__ float bf_hi(unsigned w) { return __uint_as_float(w & 0xffff0000u); }
; __device__ __forceinline__ void st_rows_f32(float* Y, int row, int col, int fr, f32x4 y0, f32x4 y1) {
;     const bool lo8 = fr < 8; const f32x4 snd = lo8 ? y1 : y0, rcv = dpp_ror8(snd);
;     const size_t a1 = lo8 ? (size_t)row * DM + col : (size_t)(row - 8) * DM + col + 4, a2 = lo8 ? (size_t)(row + 8) * DM + col : (size_t)row * DM + col + 4;
;     __builtin_nontemporal_store(lo8 ? y0 : rcv, (GAS f32x4*)(uintptr_t)(Y + a1)); __builtin_nontemporal_store(lo8 ? rcv : y1, (GAS f32x4*)(uintptr_t)(Y + a2));
; }
;     __device__ __forceinline__ void operator()(EP_ARGS) const {
;     ...
;             PLE_LD(0, 0);
; #pragma unroll
;             for (int k = 0; k < 8; ++k) { const int ai = k >> 2, m = k & 3;
;                 if (k < 7) PLE_LD(k + 1, (k + 1) & 1);
;                 __builtin_amdgcn_sched_barrier(0);
;                 { const int row = EP_ROW(ai, m); float mu, rstd; ln_unpack(tq[k & 1], mu, rstd); const size_t o = (size_t)row * DM + col;
;                     const u32x4 w_ = iw[k & 1], pw = pq[k & 1]; const f32x4 r0 = {bf_lo(w_.x), bf_hi(w_.x), bf_lo(w_.y), bf_hi(w_.y)}, r1 = {bf_lo(w_.z), bf_hi(w_.z), bf_lo(w_.w), bf_hi(w_.w)};
;                     const f32x4 x0 = (r0 - mu) * rstd * g0 + b0, x1 = (r1 - mu) * rstd * g1 + b1;
;                     const f32x4 t0 = (acc[ai][bj][m][0] - c0 * mu) * rstd + w0, t1 = (acc[ai][bj][m][1] - c1 * mu) * rstd + w1;
;                     const f32x4 p0 = {bf_lo(pw.x), bf_hi(pw.x), bf_lo(pw.y), bf_hi(pw.y)}, p1 = {bf_lo(pw.z), bf_hi(pw.z), bf_lo(pw.w), bf_hi(pw.w)};
;                     f32x4 y0, y1;
; #pragma unroll
;                     for (int j = 0; j < 4; ++j) { y0[j] = x0[j] + sigmoidf_(t0[j]) * p0[j]; y1[j] = x1[j] + sigmoidf_(t1[j]) * p1[j]; }
;                     if (Xf) st_rows_f32(Xf, row, col, fr, y0, y1); else *(GAS u32x4*)(uintptr_t)(Oh + o) = pack8(y0, y1); }
.LBB0_1807:
	v_or_b32_e32 v208, 16, v152
	v_ashrrev_i32_e32 v209, 31, v208
	v_lshlrev_b64 v[146:147], 11, v[208:209]
	v_lshl_add_u64 v[212:213], v[146:147], 0, v[176:177]
	v_lshlrev_b64 v[128:129], 1, v[212:213]
	v_lshl_add_u64 v[144:145], v[152:153], 3, s[8:9]
	v_lshl_add_u64 v[150:151], s[36:37], 0, v[128:129]
	v_lshl_add_u64 v[204:205], s[30:31], 0, v[128:129]
	global_load_dwordx2 v[216:217], v[144:145], off offset:128
	global_load_dwordx4 v[132:135], v[150:151], off
	global_load_dwordx4 v[128:131], v[204:205], off
	s_waitcnt vmcnt(6)
	v_cvt_f32_u32_e32 v190, v214
	v_cvt_f32_i32_e32 v191, v215
	s_mov_b32 s12, 0x35000000
	s_mov_b32 s13, 0x33000000
	s_waitcnt vmcnt(5)
	v_lshlrev_b32_e32 v179, 16, v140
	v_pk_mul_f32 v[190:191], v[190:191], s[12:13]
	v_and_b32_e32 v214, 0xffff0000, v140
	v_fma_f32 v140, -v191, v191, v190
	v_max_f32_e32 v140, 0, v140
	v_add_f32_e32 v140, 0x3727c5ac, v140
	v_rsq_f32_e32 v140, v140
	v_fma_f32 v104, -v88, v191, v104
	v_fma_f32 v117, -v97, v191, v117
	v_fma_f32 v116, -v96, v191, v116
	v_fma_f32 v104, v104, v140, v92
	v_mul_f32_e32 v104, 0xbfb8aa3b, v104
	v_fma_f32 v117, v117, v140, v101
	v_exp_f32_e32 v104, v104
	v_mul_f32_e32 v117, 0xbfb8aa3b, v117
	v_exp_f32_e32 v117, v117
	v_fma_f32 v116, v116, v140, v100
	v_mul_f32_e32 v116, 0xbfb8aa3b, v116
	v_exp_f32_e32 v116, v116
	v_add_f32_e32 v104, 1.0, v104
	v_rcp_f32_e32 v240, v104
	v_add_f32_e32 v104, 1.0, v117
	v_fma_f32 v106, -v90, v191, v106
	v_rcp_f32_e32 v117, v104
	v_fma_f32 v104, -v89, v191, v105
	v_fma_f32 v106, v106, v140, v94
	v_fma_f32 v119, -v99, v191, v119
	v_fma_f32 v104, v104, v140, v93
	v_mul_f32_e32 v106, 0xbfb8aa3b, v106
	v_fma_f32 v119, v119, v140, v103
	v_add_f32_e32 v116, 1.0, v116
	v_mul_f32_e32 v104, 0xbfb8aa3b, v104
	v_exp_f32_e32 v106, v106
	v_mul_f32_e32 v119, 0xbfb8aa3b, v119
	v_rcp_f32_e32 v116, v116
	s_waitcnt vmcnt(4)
	v_lshlrev_b32_e32 v242, 16, v136
	v_and_b32_e32 v243, 0xffff0000, v136
	v_exp_f32_e32 v136, v104
	v_fma_f32 v118, -v98, v191, v118
	v_exp_f32_e32 v119, v119
	v_lshlrev_b32_e32 v190, 16, v141
	v_and_b32_e32 v141, 0xffff0000, v141
	v_sub_f32_e32 v215, v214, v191
	v_sub_f32_e32 v214, v179, v191
	v_fma_f32 v118, v118, v140, v102
	v_pk_mul_f32 v[214:215], v[214:215], v[140:141] op_sel_hi:[1,0]
	v_mul_f32_e32 v118, 0xbfb8aa3b, v118
	v_pk_fma_f32 v[104:105], v[120:121], v[214:215], v[124:125]
	v_exp_f32_e32 v118, v118
	v_add_f32_e32 v106, 1.0, v106
	v_pk_fma_f32 v[104:105], v[116:117], v[242:243], v[104:105]
	v_add_f32_e32 v116, 1.0, v136
	v_rcp_f32_e32 v136, v106
	v_add_f32_e32 v106, 1.0, v119
	v_rcp_f32_e32 v119, v106
	v_fma_f32 v106, -v91, v191, v107
	v_fma_f32 v106, v106, v140, v95
	v_add_f32_e32 v118, 1.0, v118
	v_mul_f32_e32 v106, 0xbfb8aa3b, v106
	v_rcp_f32_e32 v241, v116
	v_lshlrev_b32_e32 v116, 16, v138
	v_and_b32_e32 v117, 0xffff0000, v138
	v_rcp_f32_e32 v118, v118
	v_exp_f32_e32 v138, v106
	v_lshlrev_b32_e32 v221, 16, v142
	v_and_b32_e32 v222, 0xffff0000, v142
	v_lshlrev_b32_e32 v218, 16, v143
	v_and_b32_e32 v219, 0xffff0000, v143
	v_sub_f32_e32 v143, v141, v191
	v_sub_f32_e32 v142, v190, v191
	v_pk_mul_f32 v[142:143], v[142:143], v[140:141] op_sel_hi:[1,0]
	v_lshlrev_b32_e32 v106, 16, v137
	v_pk_fma_f32 v[142:143], v[122:123], v[142:143], v[126:127]
	v_and_b32_e32 v107, 0xffff0000, v137
	v_pk_fma_f32 v[106:107], v[118:119], v[106:107], v[142:143]
	v_add_f32_e32 v118, 1.0, v138
	v_rcp_f32_e32 v137, v118
	v_sub_f32_e32 v219, v219, v191
	v_sub_f32_e32 v218, v218, v191
	v_sub_f32_e32 v223, v222, v191
	v_sub_f32_e32 v222, v221, v191
	v_pk_mul_f32 v[222:223], v[222:223], v[140:141] op_sel_hi:[1,0]
	v_pk_mul_f32 v[218:219], v[218:219], v[140:141] op_sel_hi:[1,0]
	v_lshlrev_b32_e32 v118, 16, v139
	v_pk_fma_f32 v[214:215], v[110:111], v[218:219], v[114:115]
	v_pk_fma_f32 v[218:219], v[108:109], v[222:223], v[112:113]
	v_and_b32_e32 v119, 0xffff0000, v139
	v_pk_fma_f32 v[116:117], v[240:241], v[116:117], v[218:219]
	s_and_b64 vcc, exec, s[46:47]
	v_pk_fma_f32 v[118:119], v[136:137], v[118:119], v[214:215]
	s_cbranch_vccnz .LBB0_1898
	v_cndmask_b32_e64 v139, v107, v119, s[40:41]
	v_cndmask_b32_e64 v138, v106, v118, s[40:41]
	v_cndmask_b32_e64 v137, v105, v117, s[40:41]
	v_cndmask_b32_e64 v136, v104, v116, s[40:41]
	s_nop 1
	v_mov_b32_dpp v136, v136 row_ror:8 row_mask:0xf bank_mask:0xf
	s_nop 1
	v_mov_b32_dpp v137, v137 row_ror:8 row_mask:0xf bank_mask:0xf
	s_nop 1
	v_mov_b32_dpp v138, v138 row_ror:8 row_mask:0xf bank_mask:0xf
	s_nop 1
	v_mov_b32_dpp v139, v139 row_ror:8 row_mask:0xf bank_mask:0xf
	s_and_saveexec_b64 s[12:13], s[42:43]
	s_xor_b64 s[12:13], exec, s[12:13]
	v_mov_b64_e32 v[142:143], v[118:119]
	v_lshl_add_u64 v[214:215], v[154:155], 0, v[206:207]
	v_mov_b64_e32 v[140:141], v[116:117]
	s_andn2_saveexec_b64 s[12:13], s[12:13]
	v_or_b32_e32 v140, 8, v152
	v_ashrrev_i32_e32 v141, 31, v140
	v_lshlrev_b64 v[140:141], 11, v[140:141]
	v_lshl_add_u64 v[214:215], v[140:141], 0, v[176:177]
	v_mov_b64_e32 v[142:143], v[138:139]
	v_mov_b64_e32 v[140:141], v[136:137]
	v_mov_b64_e32 v[138:139], v[106:107]
	v_mov_b64_e32 v[136:137], v[104:105]
	s_or_b64 exec, exec, s[12:13]
	v_add_u32_e32 v190, 0x78, v178
	v_ashrrev_i32_e32 v191, 31, v190
	v_lshlrev_b64 v[190:191], 11, v[190:191]
	v_lshl_add_u64 v[190:191], v[190:191], 0, v[206:207]
	v_cndmask_b32_e64 v191, v191, v211, s[40:41]
	v_cndmask_b32_e64 v190, v190, v210, s[40:41]
	v_lshl_add_u64 v[190:191], v[190:191], 2, s[4:5]
	global_store_dwordx4 v[190:191], v[136:139], off nt
	s_nop 1
	v_lshl_add_u64 v[136:137], v[214:215], 2, s[4:5]
	global_store_dwordx4 v[136:137], v[140:143], off nt
	v_lshlrev_b64 v[136:137], 12, v[152:153]
	v_lshl_add_u64 v[138:139], s[6:7], 0, v[136:137]
	s_branch .LBB0_1814

; #define GAS __attribute__((address_space(1)))
; __device__ __forceinline__ u32x4 pack8(f32x4 a, f32x4 b) { u32x4 w; w.x = cvt_pk_bf16(a[0], a[1]); w.y = cvt_pk_bf16(a[2], a[3]); w.z = cvt_pk_bf16(b[0], b[1]); w.w = cvt_pk_bf16(b[2], b[3]); return w; }
; __device__ __forceinline__ float bf_lo(unsigned w) { return __uint_as_float(w << 16); }
; __device__ __forceinline__ float bf_hi(unsigned w) { return __uint_as_float(w & 0xffff0000u); }
; __device__ __forceinline__ void st_rows_f32(float* Y, int row, int col, int fr, f32x4 y0, f32x4 y1) {
;     const bool lo8 = fr < 8; const f32x4 snd = lo8 ? y1 : y0, rcv = dpp_ror8(snd);
;     const size_t a1 = lo8 ? (size_t)row * DM + col : (size_t)(row - 8) * DM + col + 4, a2 = lo8 ? (size_t)(row + 8) * DM + col : (size_t)row * DM + col + 4;
;     __builtin_nontemporal_store(lo8 ? y0 : rcv, (GAS f32x4*)(uintptr_t)(Y + a1)); __builtin_nontemporal_store(lo8 ? rcv : y1, (GAS f32x4*)(uintptr_t)(Y + a2));
; }
;     __device__ __forceinline__ void operator()(EP_ARGS) const {
;     ...
;             PLE_LD(0, 0);
; #pragma unroll
;             for (int k = 0; k < 8; ++k) { const int ai = k >> 2, m = k & 3;
;                 if (k < 7) PLE_LD(k + 1, (k + 1) & 1);
;                 __builtin_amdgcn_sched_barrier(0);
;                 { const int row = EP_ROW(ai, m); float mu, rstd; ln_unpack(tq[k & 1], mu, rstd); const size_t o = (size_t)row * DM + col;
;                     const u32x4 w_ = iw[k & 1], pw = pq[k & 1]; const f32x4 r0 = {bf_lo(w_.x), bf_hi(w_.x), bf_lo(w_.y), bf_hi(w_.y)}, r1 = {bf_lo(w_.z), bf_hi(w_.z), bf_lo(w_.w), bf_hi(w_.w)};
;                     const f32x4 x0 = (r0 - mu) * rstd * g0 + b0, x1 = (r1 - mu) * rstd * g1 + b1;
;                     const f32x4 t0 = (acc[ai][bj][m][0] - c0 * mu) * rstd + w0, t1 = (acc[ai][bj][m][1] - c1 * mu) * rstd + w1;
;                     const f32x4 p0 = {bf_lo(pw.x), bf_hi(pw.x), bf_lo(pw.y), bf_hi(pw.y)}, p1 = {bf_lo(pw.z), bf_hi(pw.z), bf_lo(pw.w), bf_hi(pw.w)};
;                     f32x4 y0, y1;
; #pragma unroll
;                     for (int j = 0; j < 4; ++j) { y0[j] = x0[j] + sigmoidf_(t0[j]) * p0[j]; y1[j] = x1[j] + sigmoidf_(t1[j]) * p1[j]; }
;                     if (Xf) st_rows_f32(Xf, row, col, fr, y0, y1); else *(GAS u32x4*)(uintptr_t)(Oh + o) = pack8(y0, y1); }
.LBB0_1814:
	v_or_b32_e32 v210, 32, v152
	v_ashrrev_i32_e32 v211, 31, v210
	v_lshlrev_b64 v[136:137], 11, v[210:211]
	v_lshl_add_u64 v[214:215], v[136:137], 0, v[176:177]
	v_lshlrev_b64 v[104:105], 1, v[214:215]
	v_lshl_add_u64 v[140:141], s[36:37], 0, v[104:105]
	v_lshl_add_u64 v[142:143], s[30:31], 0, v[104:105]
	global_load_dwordx2 v[218:219], v[144:145], off offset:256
	global_load_dwordx4 v[116:119], v[140:141], off
	global_load_dwordx4 v[104:107], v[142:143], off
	s_waitcnt vmcnt(6)
	v_cvt_f32_u32_e32 v190, v216
	v_cvt_f32_i32_e32 v191, v217
	s_mov_b32 s12, 0x35000000
	s_mov_b32 s13, 0x33000000
	s_waitcnt vmcnt(5)
	v_lshlrev_b32_e32 v153, 16, v132
	v_pk_mul_f32 v[190:191], v[190:191], s[12:13]
	v_and_b32_e32 v179, 0xffff0000, v132
	v_fma_f32 v132, -v191, v191, v190
	v_max_f32_e32 v132, 0, v132
	v_add_f32_e32 v132, 0x3727c5ac, v132
	v_rsq_f32_e32 v132, v132
	v_fma_f32 v80, -v88, v191, v80
	v_fma_f32 v85, -v97, v191, v85
	v_fma_f32 v84, -v96, v191, v84
	v_fma_f32 v80, v80, v132, v92
	v_mul_f32_e32 v80, 0xbfb8aa3b, v80
	v_fma_f32 v85, v85, v132, v101
	v_exp_f32_e32 v80, v80
	v_mul_f32_e32 v85, 0xbfb8aa3b, v85
	v_exp_f32_e32 v85, v85
	v_fma_f32 v84, v84, v132, v100
	v_mul_f32_e32 v84, 0xbfb8aa3b, v84
	v_exp_f32_e32 v84, v84
	v_add_f32_e32 v80, 1.0, v80
	v_rcp_f32_e32 v242, v80
	v_add_f32_e32 v80, 1.0, v85
	v_fma_f32 v82, -v90, v191, v82
	v_rcp_f32_e32 v85, v80
	v_fma_f32 v80, -v89, v191, v81
	v_fma_f32 v82, v82, v132, v94
	v_fma_f32 v87, -v99, v191, v87
	v_fma_f32 v80, v80, v132, v93
	v_mul_f32_e32 v82, 0xbfb8aa3b, v82
	v_fma_f32 v87, v87, v132, v103
	v_add_f32_e32 v84, 1.0, v84
	v_mul_f32_e32 v80, 0xbfb8aa3b, v80
	v_exp_f32_e32 v82, v82
	v_mul_f32_e32 v87, 0xbfb8aa3b, v87
	v_rcp_f32_e32 v84, v84
	s_waitcnt vmcnt(4)
	v_lshlrev_b32_e32 v244, 16, v128
	v_and_b32_e32 v245, 0xffff0000, v128
	v_exp_f32_e32 v128, v80
	v_fma_f32 v86, -v98, v191, v86
	v_exp_f32_e32 v87, v87
	v_lshlrev_b32_e32 v190, 16, v133
	v_and_b32_e32 v133, 0xffff0000, v133
	v_sub_f32_e32 v217, v179, v191
	v_sub_f32_e32 v216, v153, v191
	v_fma_f32 v86, v86, v132, v102
	v_pk_mul_f32 v[216:217], v[216:217], v[132:133] op_sel_hi:[1,0]
	v_mul_f32_e32 v86, 0xbfb8aa3b, v86
	v_pk_fma_f32 v[80:81], v[120:121], v[216:217], v[124:125]
	v_exp_f32_e32 v86, v86
	v_add_f32_e32 v82, 1.0, v82
	v_pk_fma_f32 v[80:81], v[84:85], v[244:245], v[80:81]
	v_add_f32_e32 v84, 1.0, v128
	v_rcp_f32_e32 v128, v82
	v_add_f32_e32 v82, 1.0, v87
	v_rcp_f32_e32 v87, v82
	v_fma_f32 v82, -v91, v191, v83
	v_fma_f32 v82, v82, v132, v95
	v_add_f32_e32 v86, 1.0, v86
	v_mul_f32_e32 v82, 0xbfb8aa3b, v82
	v_rcp_f32_e32 v243, v84
	v_lshlrev_b32_e32 v84, 16, v130
	v_and_b32_e32 v85, 0xffff0000, v130
	v_rcp_f32_e32 v86, v86
	v_exp_f32_e32 v130, v82
	v_lshlrev_b32_e32 v221, 16, v134
	v_and_b32_e32 v240, 0xffff0000, v134
	v_lshlrev_b32_e32 v222, 16, v135
	v_and_b32_e32 v223, 0xffff0000, v135
	v_sub_f32_e32 v135, v133, v191
	v_sub_f32_e32 v134, v190, v191
	v_pk_mul_f32 v[134:135], v[134:135], v[132:133] op_sel_hi:[1,0]
	v_lshlrev_b32_e32 v82, 16, v129
	v_pk_fma_f32 v[134:135], v[122:123], v[134:135], v[126:127]
	v_and_b32_e32 v83, 0xffff0000, v129
	v_pk_fma_f32 v[82:83], v[86:87], v[82:83], v[134:135]
	v_add_f32_e32 v86, 1.0, v130
	v_rcp_f32_e32 v129, v86
	v_sub_f32_e32 v223, v223, v191
	v_sub_f32_e32 v222, v222, v191
	v_sub_f32_e32 v241, v240, v191
	v_sub_f32_e32 v240, v221, v191
	v_pk_mul_f32 v[240:241], v[240:241], v[132:133] op_sel_hi:[1,0]
	v_pk_mul_f32 v[222:223], v[222:223], v[132:133] op_sel_hi:[1,0]
	v_lshlrev_b32_e32 v86, 16, v131
	v_pk_fma_f32 v[216:217], v[110:111], v[222:223], v[114:115]
	v_pk_fma_f32 v[222:223], v[108:109], v[240:241], v[112:113]
	v_and_b32_e32 v87, 0xffff0000, v131
	v_pk_fma_f32 v[84:85], v[242:243], v[84:85], v[222:223]
	s_and_b64 vcc, exec, s[46:47]
	v_pk_fma_f32 v[86:87], v[128:129], v[86:87], v[216:217]
	s_cbranch_vccnz .LBB0_1899
	v_cndmask_b32_e64 v131, v83, v87, s[40:41]
	v_cndmask_b32_e64 v130, v82, v86, s[40:41]
	v_cndmask_b32_e64 v129, v81, v85, s[40:41]
	v_cndmask_b32_e64 v128, v80, v84, s[40:41]
	s_nop 1
	v_mov_b32_dpp v128, v128 row_ror:8 row_mask:0xf bank_mask:0xf
	s_nop 1
	v_mov_b32_dpp v129, v129 row_ror:8 row_mask:0xf bank_mask:0xf
	s_nop 1
	v_mov_b32_dpp v130, v130 row_ror:8 row_mask:0xf bank_mask:0xf
	s_nop 1
	v_mov_b32_dpp v131, v131 row_ror:8 row_mask:0xf bank_mask:0xf
	s_and_saveexec_b64 s[12:13], s[42:43]
	s_xor_b64 s[12:13], exec, s[12:13]
	v_mov_b64_e32 v[134:135], v[86:87]
	v_lshl_add_u64 v[216:217], v[146:147], 0, v[206:207]
	v_mov_b64_e32 v[132:133], v[84:85]
	s_andn2_saveexec_b64 s[12:13], s[12:13]
	v_or_b32_e32 v132, 24, v152
	v_ashrrev_i32_e32 v133, 31, v132
	v_lshlrev_b64 v[132:133], 11, v[132:133]
	v_lshl_add_u64 v[216:217], v[132:133], 0, v[176:177]
	v_mov_b64_e32 v[134:135], v[130:131]
	v_mov_b64_e32 v[132:133], v[128:129]
	v_mov_b64_e32 v[130:131], v[82:83]
	v_mov_b64_e32 v[128:129], v[80:81]
	s_or_b64 exec, exec, s[12:13]
	v_add_u32_e32 v190, 0x88, v178
	v_ashrrev_i32_e32 v191, 31, v190
	v_lshlrev_b64 v[190:191], 11, v[190:191]
	v_lshl_add_u64 v[190:191], v[190:191], 0, v[206:207]
	v_cndmask_b32_e64 v191, v191, v213, s[40:41]
	v_cndmask_b32_e64 v190, v190, v212, s[40:41]
	v_lshl_add_u64 v[190:191], v[190:191], 2, s[4:5]
	global_store_dwordx4 v[190:191], v[128:131], off nt
	s_nop 1
	v_lshl_add_u64 v[128:129], v[216:217], 2, s[4:5]
	global_store_dwordx4 v[128:129], v[132:135], off nt
	v_lshlrev_b64 v[128:129], 12, v[208:209]
	v_lshl_add_u64 v[130:131], s[6:7], 0, v[128:129]
	s_branch .LBB0_1821

; #define GAS __attribute__((address_space(1)))
; __device__ __forceinline__ u32x4 pack8(f32x4 a, f32x4 b) { u32x4 w; w.x = cvt_pk_bf16(a[0], a[1]); w.y = cvt_pk_bf16(a[2], a[3]); w.z = cvt_pk_bf16(b[0], b[1]); w.w = cvt_pk_bf16(b[2], b[3]); return w; }
; __device__ __forceinline__ float bf_lo(unsigned w) { return __uint_as_float(w << 16); }
; __device__ __forceinline__ float bf_hi(unsigned w) { return __uint_as_float(w & 0xffff0000u); }
; __device__ __forceinline__ void st_rows_f32(float* Y, int row, int col, int fr, f32x4 y0, f32x4 y1) {
;     const bool lo8 = fr < 8; const f32x4 snd = lo8 ? y1 : y0, rcv = dpp_ror8(snd);
;     const size_t a1 = lo8 ? (size_t)row * DM + col : (size_t)(row - 8) * DM + col + 4, a2 = lo8 ? (size_t)(row + 8) * DM + col : (size_t)row * DM + col + 4;
;     __builtin_nontemporal_store(lo8 ? y0 : rcv, (GAS f32x4*)(uintptr_t)(Y + a1)); __builtin_nontemporal_store(lo8 ? rcv : y1, (GAS f32x4*)(uintptr_t)(Y + a2));
; }
;     __device__ __forceinline__ void operator()(EP_ARGS) const {
;     ...
;             PLE_LD(0, 0);
; #pragma unroll
;             for (int k = 0; k < 8; ++k) { const int ai = k >> 2, m = k & 3;
;                 if (k < 7) PLE_LD(k + 1, (k + 1) & 1);
;                 __builtin_amdgcn_sched_barrier(0);
;                 { const int row = EP_ROW(ai, m); float mu, rstd; ln_unpack(tq[k & 1], mu, rstd); const size_t o = (size_t)row * DM + col;
;                     const u32x4 w_ = iw[k & 1], pw = pq[k & 1]; const f32x4 r0 = {bf_lo(w_.x), bf_hi(w_.x), bf_lo(w_.y), bf_hi(w_.y)}, r1 = {bf_lo(w_.z), bf_hi(w_.z), bf_lo(w_.w), bf_hi(w_.w)};
;                     const f32x4 x0 = (r0 - mu) * rstd * g0 + b0, x1 = (r1 - mu) * rstd * g1 + b1;
;                     const f32x4 t0 = (acc[ai][bj][m][0] - c0 * mu) * rstd + w0, t1 = (acc[ai][bj][m][1] - c1 * mu) * rstd + w1;
;                     const f32x4 p0 = {bf_lo(pw.x), bf_hi(pw.x), bf_lo(pw.y), bf_hi(pw.y)}, p1 = {bf_lo(pw.z), bf_hi(pw.z), bf_lo(pw.w), bf_hi(pw.w)};
;                     f32x4 y0, y1;
; #pragma unroll
;                     for (int j = 0; j < 4; ++j) { y0[j] = x0[j] + sigmoidf_(t0[j]) * p0[j]; y1[j] = x1[j] + sigmoidf_(t1[j]) * p1[j]; }
;                     if (Xf) st_rows_f32(Xf, row, col, fr, y0, y1); else *(GAS u32x4*)(uintptr_t)(Oh + o) = pack8(y0, y1); }
.LBB0_1821:
	v_or_b32_e32 v208, 48, v152
	v_ashrrev_i32_e32 v209, 31, v208
	v_lshlrev_b64 v[128:129], 11, v[208:209]
	v_lshl_add_u64 v[212:213], v[128:129], 0, v[176:177]
	v_lshlrev_b64 v[80:81], 1, v[212:213]
	v_lshl_add_u64 v[132:133], s[36:37], 0, v[80:81]
	v_lshl_add_u64 v[134:135], s[30:31], 0, v[80:81]
	global_load_dwordx2 v[216:217], v[144:145], off offset:384
	global_load_dwordx4 v[84:87], v[132:133], off
	global_load_dwordx4 v[80:83], v[134:135], off
	s_waitcnt vmcnt(6)
	v_cvt_f32_u32_e32 v190, v218
	v_cvt_f32_i32_e32 v191, v219
	s_mov_b32 s12, 0x35000000
	s_mov_b32 s13, 0x33000000
	s_waitcnt vmcnt(5)
	v_lshlrev_b32_e32 v153, 16, v116
	v_pk_mul_f32 v[190:191], v[190:191], s[12:13]
	v_and_b32_e32 v179, 0xffff0000, v116
	v_fma_f32 v116, -v191, v191, v190
	v_max_f32_e32 v116, 0, v116
	v_add_f32_e32 v116, 0x3727c5ac, v116
	v_rsq_f32_e32 v116, v116
	v_fma_f32 v72, -v88, v191, v72
	v_fma_f32 v77, -v97, v191, v77
	v_fma_f32 v76, -v96, v191, v76
	v_fma_f32 v72, v72, v116, v92
	v_mul_f32_e32 v72, 0xbfb8aa3b, v72
	v_fma_f32 v77, v77, v116, v101
	v_exp_f32_e32 v72, v72
	v_mul_f32_e32 v77, 0xbfb8aa3b, v77
	v_exp_f32_e32 v77, v77
	v_fma_f32 v76, v76, v116, v100
	v_mul_f32_e32 v76, 0xbfb8aa3b, v76
	v_exp_f32_e32 v76, v76
	v_add_f32_e32 v72, 1.0, v72
	v_rcp_f32_e32 v242, v72
	v_add_f32_e32 v72, 1.0, v77
	v_fma_f32 v74, -v90, v191, v74
	v_rcp_f32_e32 v77, v72
	v_fma_f32 v72, -v89, v191, v73
	v_fma_f32 v74, v74, v116, v94
	v_fma_f32 v79, -v99, v191, v79
	v_fma_f32 v72, v72, v116, v93
	v_mul_f32_e32 v74, 0xbfb8aa3b, v74
	v_fma_f32 v79, v79, v116, v103
	v_add_f32_e32 v76, 1.0, v76
	v_mul_f32_e32 v72, 0xbfb8aa3b, v72
	v_exp_f32_e32 v74, v74
	v_mul_f32_e32 v79, 0xbfb8aa3b, v79
	v_rcp_f32_e32 v76, v76
	s_waitcnt vmcnt(4)
	v_lshlrev_b32_e32 v244, 16, v104
	v_and_b32_e32 v245, 0xffff0000, v104
	v_exp_f32_e32 v104, v72
	v_fma_f32 v78, -v98, v191, v78
	v_exp_f32_e32 v79, v79
	v_lshlrev_b32_e32 v190, 16, v117
	v_and_b32_e32 v117, 0xffff0000, v117
	v_sub_f32_e32 v219, v179, v191
	v_sub_f32_e32 v218, v153, v191
	v_fma_f32 v78, v78, v116, v102
	v_pk_mul_f32 v[218:219], v[218:219], v[116:117] op_sel_hi:[1,0]
	v_mul_f32_e32 v78, 0xbfb8aa3b, v78
	v_pk_fma_f32 v[72:73], v[120:121], v[218:219], v[124:125]
	v_exp_f32_e32 v78, v78
	v_add_f32_e32 v74, 1.0, v74
	v_pk_fma_f32 v[72:73], v[76:77], v[244:245], v[72:73]
	v_add_f32_e32 v76, 1.0, v104
	v_rcp_f32_e32 v104, v74
	v_add_f32_e32 v74, 1.0, v79
	v_rcp_f32_e32 v79, v74
	v_fma_f32 v74, -v91, v191, v75
	v_fma_f32 v74, v74, v116, v95
	v_add_f32_e32 v78, 1.0, v78
	v_mul_f32_e32 v74, 0xbfb8aa3b, v74
	v_rcp_f32_e32 v243, v76
	v_lshlrev_b32_e32 v76, 16, v106
	v_and_b32_e32 v77, 0xffff0000, v106
	v_rcp_f32_e32 v78, v78
	v_exp_f32_e32 v106, v74
	v_lshlrev_b32_e32 v221, 16, v118
	v_and_b32_e32 v240, 0xffff0000, v118
	v_lshlrev_b32_e32 v222, 16, v119
	v_and_b32_e32 v223, 0xffff0000, v119
	v_sub_f32_e32 v119, v117, v191
	v_sub_f32_e32 v118, v190, v191
	v_pk_mul_f32 v[118:119], v[118:119], v[116:117] op_sel_hi:[1,0]
	v_lshlrev_b32_e32 v74, 16, v105
	v_pk_fma_f32 v[118:119], v[122:123], v[118:119], v[126:127]
	v_and_b32_e32 v75, 0xffff0000, v105
	v_pk_fma_f32 v[74:75], v[78:79], v[74:75], v[118:119]
	v_add_f32_e32 v78, 1.0, v106
	v_rcp_f32_e32 v105, v78
	v_sub_f32_e32 v223, v223, v191
	v_sub_f32_e32 v222, v222, v191
	v_sub_f32_e32 v241, v240, v191
	v_sub_f32_e32 v240, v221, v191
	v_pk_mul_f32 v[240:241], v[240:241], v[116:117] op_sel_hi:[1,0]
	v_pk_mul_f32 v[222:223], v[222:223], v[116:117] op_sel_hi:[1,0]
	v_lshlrev_b32_e32 v78, 16, v107
	v_pk_fma_f32 v[218:219], v[110:111], v[222:223], v[114:115]
	v_pk_fma_f32 v[222:223], v[108:109], v[240:241], v[112:113]
	v_and_b32_e32 v79, 0xffff0000, v107
	v_pk_fma_f32 v[76:77], v[242:243], v[76:77], v[222:223]
	s_and_b64 vcc, exec, s[46:47]
	v_pk_fma_f32 v[78:79], v[104:105], v[78:79], v[218:219]
	s_cbranch_vccnz .LBB0_1900
	v_cndmask_b32_e64 v107, v75, v79, s[40:41]
	v_cndmask_b32_e64 v106, v74, v78, s[40:41]
	v_cndmask_b32_e64 v105, v73, v77, s[40:41]
	v_cndmask_b32_e64 v104, v72, v76, s[40:41]
	s_nop 1
	v_mov_b32_dpp v104, v104 row_ror:8 row_mask:0xf bank_mask:0xf
	s_nop 1
	v_mov_b32_dpp v105, v105 row_ror:8 row_mask:0xf bank_mask:0xf
	s_nop 1
	v_mov_b32_dpp v106, v106 row_ror:8 row_mask:0xf bank_mask:0xf
	s_nop 1
	v_mov_b32_dpp v107, v107 row_ror:8 row_mask:0xf bank_mask:0xf
	s_and_saveexec_b64 s[12:13], s[42:43]
	s_xor_b64 s[12:13], exec, s[12:13]
	v_mov_b64_e32 v[118:119], v[78:79]
	v_lshl_add_u64 v[218:219], v[136:137], 0, v[206:207]
	v_mov_b64_e32 v[116:117], v[76:77]
	s_andn2_saveexec_b64 s[12:13], s[12:13]
	v_or_b32_e32 v116, 40, v152
	v_ashrrev_i32_e32 v117, 31, v116
	v_lshlrev_b64 v[116:117], 11, v[116:117]
	v_lshl_add_u64 v[218:219], v[116:117], 0, v[176:177]
	v_mov_b64_e32 v[118:119], v[106:107]
	v_mov_b64_e32 v[116:117], v[104:105]
	v_mov_b64_e32 v[106:107], v[74:75]
	v_mov_b64_e32 v[104:105], v[72:73]
	s_or_b64 exec, exec, s[12:13]
	v_add_u32_e32 v190, 0x98, v178
	v_ashrrev_i32_e32 v191, 31, v190
	v_lshlrev_b64 v[190:191], 11, v[190:191]
	v_lshl_add_u64 v[190:191], v[190:191], 0, v[206:207]
	v_cndmask_b32_e64 v191, v191, v215, s[40:41]
	v_cndmask_b32_e64 v190, v190, v214, s[40:41]
	v_lshl_add_u64 v[190:191], v[190:191], 2, s[4:5]
	global_store_dwordx4 v[190:191], v[104:107], off nt
	s_nop 1
	v_lshl_add_u64 v[104:105], v[218:219], 2, s[4:5]
	global_store_dwordx4 v[104:105], v[116:119], off nt
	v_lshlrev_b64 v[104:105], 12, v[210:211]
	s_nop 0
	v_lshl_add_u64 v[116:117], s[6:7], 0, v[104:105]
	s_branch .LBB0_1828

; #define GAS __attribute__((address_space(1)))
; __device__ __forceinline__ u32x4 pack8(f32x4 a, f32x4 b) { u32x4 w; w.x = cvt_pk_bf16(a[0], a[1]); w.y = cvt_pk_bf16(a[2], a[3]); w.z = cvt_pk_bf16(b[0], b[1]); w.w = cvt_pk_bf16(b[2], b[3]); return w; }
; __device__ __forceinline__ float bf_lo(unsigned w) { return __uint_as_float(w << 16); }
; __device__ __forceinline__ float bf_hi(unsigned w) { return __uint_as_float(w & 0xffff0000u); }
; __device__ __forceinline__ float sigmoidf_(float x) { return __builtin_amdgcn_rcpf(1.0f + __builtin_amdgcn_exp2f(-x * LOG2E)); }
; __device__ __forceinline__ f32x4 dpp_ror8(f32x4 v) { f32x4 r; r.x = dpp_ror8_1(v.x); r.y = dpp_ror8_1(v.y); r.z = dpp_ror8_1(v.z); r.w = dpp_ror8_1(v.w); return r; }
; __device__ __forceinline__ void st_rows_f32(float* Y, int row, int col, int fr, f32x4 y0, f32x4 y1) {
;     const bool lo8 = fr < 8; const f32x4 snd = lo8 ? y1 : y0, rcv = dpp_ror8(snd);
;     const size_t a1 = lo8 ? (size_t)row * DM + col : (size_t)(row - 8) * DM + col + 4, a2 = lo8 ? (size_t)(row + 8) * DM + col : (size_t)row * DM + col + 4;
;     __builtin_nontemporal_store(lo8 ? y0 : rcv, (GAS f32x4*)(uintptr_t)(Y + a1)); __builtin_nontemporal_store(lo8 ? rcv : y1, (GAS f32x4*)(uintptr_t)(Y + a2));
; }
;     __device__ __forceinline__ void operator()(EP_ARGS) const {
;     ...
;                 { const int row = EP_ROW(ai, m); float mu, rstd; ln_unpack(tq[k & 1], mu, rstd); const size_t o = (size_t)row * DM + col;
;                     const u32x4 w_ = iw[k & 1], pw = pq[k & 1]; const f32x4 r0 = {bf_lo(w_.x), bf_hi(w_.x), bf_lo(w_.y), bf_hi(w_.y)}, r1 = {bf_lo(w_.z), bf_hi(w_.z), bf_lo(w_.w), bf_hi(w_.w)};
;                     const f32x4 x0 = (r0 - mu) * rstd * g0 + b0, x1 = (r1 - mu) * rstd * g1 + b1;
;                     const f32x4 t0 = (acc[ai][bj][m][0] - c0 * mu) * rstd + w0, t1 = (acc[ai][bj][m][1] - c1 * mu) * rstd + w1;
;                     const f32x4 p0 = {bf_lo(pw.x), bf_hi(pw.x), bf_lo(pw.y), bf_hi(pw.y)}, p1 = {bf_lo(pw.z), bf_hi(pw.z), bf_lo(pw.w), bf_hi(pw.w)};
;                     f32x4 y0, y1;
; #pragma unroll
;                     for (int j = 0; j < 4; ++j) { y0[j] = x0[j] + sigmoidf_(t0[j]) * p0[j]; y1[j] = x1[j] + sigmoidf_(t1[j]) * p1[j]; }
;                     if (Xf) st_rows_f32(Xf, row, col, fr, y0, y1); else *(GAS u32x4*)(uintptr_t)(Oh + o) = pack8(y0, y1); }
.LBB0_1828:
	s_waitcnt vmcnt(3)
	s_nop 0
	v_cvt_f32_u32_e32 v72, v216
	v_cvt_f32_i32_e32 v73, v217
	s_mov_b32 s12, 0x35000000
	s_mov_b32 s13, 0x33000000
	s_waitcnt vmcnt(2)
	v_lshlrev_b32_e32 v76, 16, v84
	v_pk_mul_f32 v[72:73], v[72:73], s[12:13]
	v_and_b32_e32 v77, 0xffff0000, v84
	v_fma_f32 v72, -v73, v73, v72
	v_max_f32_e32 v72, 0, v72
	v_add_f32_e32 v72, 0x3727c5ac, v72
	v_rsq_f32_e32 v72, v72
	v_fma_f32 v64, -v88, v73, v64
	v_fma_f32 v69, -v97, v73, v69
	v_fma_f32 v68, -v96, v73, v68
	v_fma_f32 v64, v64, v72, v92
	v_mul_f32_e32 v64, 0xbfb8aa3b, v64
	v_fma_f32 v69, v69, v72, v101
	v_exp_f32_e32 v64, v64
	v_mul_f32_e32 v69, 0xbfb8aa3b, v69
	v_exp_f32_e32 v69, v69
	v_fma_f32 v68, v68, v72, v100
	v_mul_f32_e32 v68, 0xbfb8aa3b, v68
	v_exp_f32_e32 v68, v68
	v_add_f32_e32 v64, 1.0, v64
	v_lshlrev_b32_e32 v74, 16, v85
	v_and_b32_e32 v75, 0xffff0000, v85
	v_lshlrev_b32_e32 v84, 16, v86
	v_and_b32_e32 v85, 0xffff0000, v86
	v_rcp_f32_e32 v86, v64
	v_add_f32_e32 v64, 1.0, v69
	v_rcp_f32_e32 v69, v64
	v_fma_f32 v64, -v89, v73, v65
	v_fma_f32 v64, v64, v72, v93
	v_add_f32_e32 v68, 1.0, v68
	v_mul_f32_e32 v64, 0xbfb8aa3b, v64
	v_rcp_f32_e32 v68, v68
	s_waitcnt vmcnt(1)
	v_lshlrev_b32_e32 v96, 16, v80
	v_and_b32_e32 v97, 0xffff0000, v80
	v_exp_f32_e32 v80, v64
	v_sub_f32_e32 v77, v77, v73
	v_sub_f32_e32 v76, v76, v73
	v_fma_f32 v66, -v90, v73, v66
	v_pk_mul_f32 v[76:77], v[76:77], v[72:73] op_sel_hi:[1,0]
	v_fma_f32 v66, v66, v72, v94
	v_fma_f32 v71, -v99, v73, v71
	v_pk_fma_f32 v[64:65], v[120:121], v[76:77], v[124:125]
	v_mul_f32_e32 v66, 0xbfb8aa3b, v66
	v_fmac_f32_e32 v103, v71, v72
	v_pk_fma_f32 v[64:65], v[68:69], v[96:97], v[64:65]
	v_add_f32_e32 v68, 1.0, v80
	v_exp_f32_e32 v66, v66
	v_mul_f32_e32 v71, 0xbfb8aa3b, v103
	v_lshlrev_b32_e32 v78, 16, v87
	v_and_b32_e32 v79, 0xffff0000, v87
	v_rcp_f32_e32 v87, v68
	v_fma_f32 v70, -v98, v73, v70
	v_exp_f32_e32 v71, v71
	v_sub_f32_e32 v79, v79, v73
	v_sub_f32_e32 v78, v78, v73
	v_sub_f32_e32 v85, v85, v73
	v_sub_f32_e32 v84, v84, v73
	v_fma_f32 v70, v70, v72, v102
	v_pk_mul_f32 v[84:85], v[84:85], v[72:73] op_sel_hi:[1,0]
	v_pk_mul_f32 v[78:79], v[78:79], v[72:73] op_sel_hi:[1,0]
	v_mul_f32_e32 v70, 0xbfb8aa3b, v70
	v_lshlrev_b32_e32 v68, 16, v82
	v_and_b32_e32 v69, 0xffff0000, v82
	v_exp_f32_e32 v70, v70
	v_pk_fma_f32 v[76:77], v[110:111], v[78:79], v[114:115]
	v_pk_fma_f32 v[78:79], v[108:109], v[84:85], v[112:113]
	v_add_f32_e32 v66, 1.0, v66
	v_pk_fma_f32 v[68:69], v[86:87], v[68:69], v[78:79]
	v_rcp_f32_e32 v78, v66
	v_add_f32_e32 v66, 1.0, v71
	v_rcp_f32_e32 v71, v66
	v_fma_f32 v66, -v91, v73, v67
	v_fmac_f32_e32 v95, v66, v72
	v_sub_f32_e32 v75, v75, v73
	v_sub_f32_e32 v74, v74, v73
	v_add_f32_e32 v70, 1.0, v70
	v_mul_f32_e32 v66, 0xbfb8aa3b, v95
	v_pk_mul_f32 v[74:75], v[74:75], v[72:73] op_sel_hi:[1,0]
	v_rcp_f32_e32 v70, v70
	v_exp_f32_e32 v72, v66
	v_pk_fma_f32 v[74:75], v[122:123], v[74:75], v[126:127]
	v_lshlrev_b32_e32 v66, 16, v81
	v_and_b32_e32 v67, 0xffff0000, v81
	v_pk_fma_f32 v[66:67], v[70:71], v[66:67], v[74:75]
	v_add_f32_e32 v70, 1.0, v72
	v_rcp_f32_e32 v79, v70
	v_lshlrev_b32_e32 v70, 16, v83
	v_and_b32_e32 v71, 0xffff0000, v83
	s_and_b64 vcc, exec, s[46:47]
	v_pk_fma_f32 v[70:71], v[78:79], v[70:71], v[76:77]
	s_cbranch_vccnz .LBB0_1901
	v_cndmask_b32_e64 v75, v67, v71, s[40:41]
	v_cndmask_b32_e64 v74, v66, v70, s[40:41]
	v_cndmask_b32_e64 v73, v65, v69, s[40:41]
	v_cndmask_b32_e64 v72, v64, v68, s[40:41]
	s_nop 1
	v_mov_b32_dpp v72, v72 row_ror:8 row_mask:0xf bank_mask:0xf
	s_nop 1
	v_mov_b32_dpp v73, v73 row_ror:8 row_mask:0xf bank_mask:0xf
	s_nop 1
	v_mov_b32_dpp v74, v74 row_ror:8 row_mask:0xf bank_mask:0xf
	s_nop 1
	v_mov_b32_dpp v75, v75 row_ror:8 row_mask:0xf bank_mask:0xf
	s_and_saveexec_b64 s[12:13], s[42:43]
	s_xor_b64 s[12:13], exec, s[12:13]
	v_mov_b64_e32 v[78:79], v[70:71]
	v_lshl_add_u64 v[80:81], v[128:129], 0, v[206:207]
	v_mov_b64_e32 v[76:77], v[68:69]
	s_andn2_saveexec_b64 s[12:13], s[12:13]
	v_or_b32_e32 v76, 56, v152
	v_ashrrev_i32_e32 v77, 31, v76
	v_lshlrev_b64 v[76:77], 11, v[76:77]
	v_lshl_add_u64 v[80:81], v[76:77], 0, v[176:177]
	v_mov_b64_e32 v[78:79], v[74:75]
	v_mov_b64_e32 v[76:77], v[72:73]
	v_mov_b64_e32 v[74:75], v[66:67]
	v_mov_b64_e32 v[72:73], v[64:65]
	s_or_b64 exec, exec, s[12:13]
	v_add_u32_e32 v82, 0xa8, v178
	v_ashrrev_i32_e32 v83, 31, v82
	v_lshlrev_b64 v[82:83], 11, v[82:83]
	v_lshl_add_u64 v[82:83], v[82:83], 0, v[206:207]
	v_cndmask_b32_e64 v83, v83, v213, s[40:41]
	v_cndmask_b32_e64 v82, v82, v212, s[40:41]
	v_lshl_add_u64 v[82:83], v[82:83], 2, s[4:5]
	global_store_dwordx4 v[82:83], v[72:75], off nt
	s_nop 1
	v_lshl_add_u64 v[72:73], v[80:81], 2, s[4:5]
	global_store_dwordx4 v[72:73], v[76:79], off nt
	v_lshlrev_b64 v[72:73], 12, v[208:209]
	v_lshl_add_u64 v[112:113], s[6:7], 0, v[72:73]
	s_branch .LBB0_1835

; #define GAS __attribute__((address_space(1)))
; __device__ __forceinline__ u32x4 pack8(f32x4 a, f32x4 b) { u32x4 w; w.x = cvt_pk_bf16(a[0], a[1]); w.y = cvt_pk_bf16(a[2], a[3]); w.z = cvt_pk_bf16(b[0], b[1]); w.w = cvt_pk_bf16(b[2], b[3]); return w; }
; __device__ __forceinline__ float bf_lo(unsigned w) { return __uint_as_float(w << 16); }
; __device__ __forceinline__ float bf_hi(unsigned w) { return __uint_as_float(w & 0xffff0000u); }
; __device__ __forceinline__ void st_rows_f32(float* Y, int row, int col, int fr, f32x4 y0, f32x4 y1) {
;     const bool lo8 = fr < 8; const f32x4 snd = lo8 ? y1 : y0, rcv = dpp_ror8(snd);
;     const size_t a1 = lo8 ? (size_t)row * DM + col : (size_t)(row - 8) * DM + col + 4, a2 = lo8 ? (size_t)(row + 8) * DM + col : (size_t)row * DM + col + 4;
;     __builtin_nontemporal_store(lo8 ? y0 : rcv, (GAS f32x4*)(uintptr_t)(Y + a1)); __builtin_nontemporal_store(lo8 ? rcv : y1, (GAS f32x4*)(uintptr_t)(Y + a2));
; }
;     __device__ __forceinline__ void operator()(EP_ARGS) const {
;     ...
;             PLE_LD(0, 0);
; #pragma unroll
;             for (int k = 0; k < 8; ++k) { const int ai = k >> 2, m = k & 3;
;                 if (k < 7) PLE_LD(k + 1, (k + 1) & 1);
;                 __builtin_amdgcn_sched_barrier(0);
;                 { const int row = EP_ROW(ai, m); float mu, rstd; ln_unpack(tq[k & 1], mu, rstd); const size_t o = (size_t)row * DM + col;
;                     const u32x4 w_ = iw[k & 1], pw = pq[k & 1]; const f32x4 r0 = {bf_lo(w_.x), bf_hi(w_.x), bf_lo(w_.y), bf_hi(w_.y)}, r1 = {bf_lo(w_.z), bf_hi(w_.z), bf_lo(w_.w), bf_hi(w_.w)};
;                     const f32x4 x0 = (r0 - mu) * rstd * g0 + b0, x1 = (r1 - mu) * rstd * g1 + b1;
;                     const f32x4 t0 = (acc[ai][bj][m][0] - c0 * mu) * rstd + w0, t1 = (acc[ai][bj][m][1] - c1 * mu) * rstd + w1;
;                     const f32x4 p0 = {bf_lo(pw.x), bf_hi(pw.x), bf_lo(pw.y), bf_hi(pw.y)}, p1 = {bf_lo(pw.z), bf_hi(pw.z), bf_lo(pw.w), bf_hi(pw.w)};
;                     f32x4 y0, y1;
; #pragma unroll
;                     for (int j = 0; j < 4; ++j) { y0[j] = x0[j] + sigmoidf_(t0[j]) * p0[j]; y1[j] = x1[j] + sigmoidf_(t1[j]) * p1[j]; }
;                     if (Xf) st_rows_f32(Xf, row, col, fr, y0, y1); else *(GAS u32x4*)(uintptr_t)(Oh + o) = pack8(y0, y1); }
.LBB0_1849:
	global_load_dwordx2 v[96:97], v[182:183], off offset:384
	s_nop 0
	global_load_dwordx4 v[52:55], v[164:165], off offset:256
	global_load_dwordx4 v[48:51], v[166:167], off offset:256
	s_waitcnt vmcnt(6)
	v_cvt_f32_u32_e32 v98, v104
	v_cvt_f32_i32_e32 v99, v105
	s_mov_b32 s12, 0x35000000
	s_mov_b32 s13, 0x33000000
	s_waitcnt vmcnt(5)
	v_lshlrev_b32_e32 v100, 16, v60
	v_pk_mul_f32 v[98:99], v[98:99], s[12:13]
	v_and_b32_e32 v101, 0xffff0000, v60
	v_fma_f32 v60, -v99, v99, v98
	v_max_f32_e32 v60, 0, v60
	v_add_f32_e32 v60, 0x3727c5ac, v60
	v_rsq_f32_e32 v60, v60
	v_fma_f32 v40, -v64, v99, v40
	v_fma_f32 v45, -v73, v99, v45
	v_fma_f32 v44, -v72, v99, v44
	v_fma_f32 v40, v40, v60, v68
	v_mul_f32_e32 v40, 0xbfb8aa3b, v40
	v_fma_f32 v45, v45, v60, v77
	v_exp_f32_e32 v40, v40
	v_mul_f32_e32 v45, 0xbfb8aa3b, v45
	v_exp_f32_e32 v45, v45
	v_fma_f32 v44, v44, v60, v76
	v_mul_f32_e32 v44, 0xbfb8aa3b, v44
	v_exp_f32_e32 v44, v44
	v_add_f32_e32 v40, 1.0, v40
	v_rcp_f32_e32 v106, v40
	v_add_f32_e32 v40, 1.0, v45
	v_fma_f32 v42, -v66, v99, v42
	v_rcp_f32_e32 v45, v40
	v_fma_f32 v40, -v65, v99, v41
	v_fma_f32 v42, v42, v60, v70
	v_fma_f32 v47, -v75, v99, v47
	v_fma_f32 v40, v40, v60, v69
	v_mul_f32_e32 v42, 0xbfb8aa3b, v42
	v_fma_f32 v47, v47, v60, v79
	v_add_f32_e32 v44, 1.0, v44
	v_mul_f32_e32 v40, 0xbfb8aa3b, v40
	v_exp_f32_e32 v42, v42
	v_mul_f32_e32 v47, 0xbfb8aa3b, v47
	v_rcp_f32_e32 v44, v44
	s_waitcnt vmcnt(4)
	v_lshlrev_b32_e32 v108, 16, v56
	v_and_b32_e32 v109, 0xffff0000, v56
	v_exp_f32_e32 v56, v40
	v_fma_f32 v46, -v74, v99, v46
	v_exp_f32_e32 v47, v47
	v_lshlrev_b32_e32 v98, 16, v61
	v_and_b32_e32 v61, 0xffff0000, v61
	v_sub_f32_e32 v101, v101, v99
	v_sub_f32_e32 v100, v100, v99
	v_fma_f32 v46, v46, v60, v78
	v_pk_mul_f32 v[100:101], v[100:101], v[60:61] op_sel_hi:[1,0]
	v_mul_f32_e32 v46, 0xbfb8aa3b, v46
	v_pk_fma_f32 v[40:41], v[88:89], v[100:101], v[92:93]
	v_exp_f32_e32 v46, v46
	v_add_f32_e32 v42, 1.0, v42
	v_pk_fma_f32 v[40:41], v[44:45], v[108:109], v[40:41]
	v_add_f32_e32 v44, 1.0, v56
	v_rcp_f32_e32 v56, v42
	v_add_f32_e32 v42, 1.0, v47
	v_rcp_f32_e32 v47, v42
	v_fma_f32 v42, -v67, v99, v43
	v_fma_f32 v42, v42, v60, v71
	v_add_f32_e32 v46, 1.0, v46
	v_mul_f32_e32 v42, 0xbfb8aa3b, v42
	v_rcp_f32_e32 v107, v44
	v_lshlrev_b32_e32 v44, 16, v58
	v_and_b32_e32 v45, 0xffff0000, v58
	v_rcp_f32_e32 v46, v46
	v_exp_f32_e32 v58, v42
	v_lshlrev_b32_e32 v104, 16, v62
	v_and_b32_e32 v105, 0xffff0000, v62
	v_lshlrev_b32_e32 v102, 16, v63
	v_and_b32_e32 v103, 0xffff0000, v63
	v_sub_f32_e32 v63, v61, v99
	v_sub_f32_e32 v62, v98, v99
	v_pk_mul_f32 v[62:63], v[62:63], v[60:61] op_sel_hi:[1,0]
	v_lshlrev_b32_e32 v42, 16, v57
	v_pk_fma_f32 v[62:63], v[90:91], v[62:63], v[94:95]
	v_and_b32_e32 v43, 0xffff0000, v57
	v_pk_fma_f32 v[42:43], v[46:47], v[42:43], v[62:63]
	v_add_f32_e32 v46, 1.0, v58
	v_rcp_f32_e32 v57, v46
	v_sub_f32_e32 v103, v103, v99
	v_sub_f32_e32 v102, v102, v99
	v_sub_f32_e32 v105, v105, v99
	v_sub_f32_e32 v104, v104, v99
	v_pk_mul_f32 v[104:105], v[104:105], v[60:61] op_sel_hi:[1,0]
	v_pk_mul_f32 v[102:103], v[102:103], v[60:61] op_sel_hi:[1,0]
	v_lshlrev_b32_e32 v46, 16, v59
	v_pk_fma_f32 v[100:101], v[82:83], v[102:103], v[86:87]
	v_pk_fma_f32 v[102:103], v[80:81], v[104:105], v[84:85]
	v_and_b32_e32 v47, 0xffff0000, v59
	v_pk_fma_f32 v[44:45], v[106:107], v[44:45], v[102:103]
	s_and_b64 vcc, exec, s[46:47]
	v_pk_fma_f32 v[46:47], v[56:57], v[46:47], v[100:101]
	s_cbranch_vccnz .LBB0_1904
	v_cndmask_b32_e64 v59, v43, v47, s[40:41]
	v_cndmask_b32_e64 v58, v42, v46, s[40:41]
	v_cndmask_b32_e64 v57, v41, v45, s[40:41]
	v_cndmask_b32_e64 v56, v40, v44, s[40:41]
	s_nop 1
	v_mov_b32_dpp v56, v56 row_ror:8 row_mask:0xf bank_mask:0xf
	s_nop 1
	v_mov_b32_dpp v57, v57 row_ror:8 row_mask:0xf bank_mask:0xf
	s_nop 1
	v_mov_b32_dpp v58, v58 row_ror:8 row_mask:0xf bank_mask:0xf
	s_nop 1
	v_mov_b32_dpp v59, v59 row_ror:8 row_mask:0xf bank_mask:0xf
	s_and_saveexec_b64 s[12:13], s[42:43]
	s_xor_b64 s[12:13], exec, s[12:13]
	v_mov_b64_e32 v[62:63], v[46:47]
	v_lshl_add_u64 v[98:99], v[168:169], 0, v[118:119]
	v_mov_b64_e32 v[60:61], v[44:45]
	s_andn2_saveexec_b64 s[12:13], s[12:13]
	v_or_b32_e32 v60, 40, v178
	v_ashrrev_i32_e32 v61, 31, v60
	v_lshlrev_b64 v[60:61], 11, v[60:61]
	v_lshl_add_u64 v[98:99], v[60:61], 0, v[114:115]
	v_mov_b64_e32 v[62:63], v[58:59]
	v_mov_b64_e32 v[60:61], v[56:57]
	v_mov_b64_e32 v[58:59], v[42:43]
	v_mov_b64_e32 v[56:57], v[40:41]
	s_or_b64 exec, exec, s[12:13]
	v_lshl_add_u64 v[102:103], v[180:181], 0, v[118:119]
	s_mov_b64 s[12:13], 0xc000
	v_lshl_add_u64 v[100:101], v[168:169], 0, v[114:115]
	v_lshl_add_u64 v[102:103], v[102:103], 0, s[12:13]
	v_cndmask_b32_e64 v101, v103, v101, s[40:41]
	v_cndmask_b32_e64 v100, v102, v100, s[40:41]
	v_lshl_add_u64 v[100:101], v[100:101], 2, s[4:5]
	global_store_dwordx4 v[100:101], v[56:59], off nt
	s_nop 1
	v_lshl_add_u64 v[56:57], v[98:99], 2, s[4:5]
	global_store_dwordx4 v[56:57], v[60:63], off nt
	s_branch .LBB0_1856

; #define GAS __attribute__((address_space(1)))
; __device__ __forceinline__ u32x4 pack8(f32x4 a, f32x4 b) { u32x4 w; w.x = cvt_pk_bf16(a[0], a[1]); w.y = cvt_pk_bf16(a[2], a[3]); w.z = cvt_pk_bf16(b[0], b[1]); w.w = cvt_pk_bf16(b[2], b[3]); return w; }
; __device__ __forceinline__ float bf_lo(unsigned w) { return __uint_as_float(w << 16); }
; __device__ __forceinline__ float bf_hi(unsigned w) { return __uint_as_float(w & 0xffff0000u); }
; __device__ __forceinline__ void st_rows_f32(float* Y, int row, int col, int fr, f32x4 y0, f32x4 y1) {
;     const bool lo8 = fr < 8; const f32x4 snd = lo8 ? y1 : y0, rcv = dpp_ror8(snd);
;     const size_t a1 = lo8 ? (size_t)row * DM + col : (size_t)(row - 8) * DM + col + 4, a2 = lo8 ? (size_t)(row + 8) * DM + col : (size_t)row * DM + col + 4;
;     __builtin_nontemporal_store(lo8 ? y0 : rcv, (GAS f32x4*)(uintptr_t)(Y + a1)); __builtin_nontemporal_store(lo8 ? rcv : y1, (GAS f32x4*)(uintptr_t)(Y + a2));
; }
;     __device__ __forceinline__ void operator()(EP_ARGS) const {
;     ...
;             PLE_LD(0, 0);
; #pragma unroll
;             for (int k = 0; k < 8; ++k) { const int ai = k >> 2, m = k & 3;
;                 if (k < 7) PLE_LD(k + 1, (k + 1) & 1);
;                 __builtin_amdgcn_sched_barrier(0);
;                 { const int row = EP_ROW(ai, m); float mu, rstd; ln_unpack(tq[k & 1], mu, rstd); const size_t o = (size_t)row * DM + col;
;                     const u32x4 w_ = iw[k & 1], pw = pq[k & 1]; const f32x4 r0 = {bf_lo(w_.x), bf_hi(w_.x), bf_lo(w_.y), bf_hi(w_.y)}, r1 = {bf_lo(w_.z), bf_hi(w_.z), bf_lo(w_.w), bf_hi(w_.w)};
;                     const f32x4 x0 = (r0 - mu) * rstd * g0 + b0, x1 = (r1 - mu) * rstd * g1 + b1;
;                     const f32x4 t0 = (acc[ai][bj][m][0] - c0 * mu) * rstd + w0, t1 = (acc[ai][bj][m][1] - c1 * mu) * rstd + w1;
;                     const f32x4 p0 = {bf_lo(pw.x), bf_hi(pw.x), bf_lo(pw.y), bf_hi(pw.y)}, p1 = {bf_lo(pw.z), bf_hi(pw.z), bf_lo(pw.w), bf_hi(pw.w)};
;                     f32x4 y0, y1;
; #pragma unroll
;                     for (int j = 0; j < 4; ++j) { y0[j] = x0[j] + sigmoidf_(t0[j]) * p0[j]; y1[j] = x1[j] + sigmoidf_(t1[j]) * p1[j]; }
;                     if (Xf) st_rows_f32(Xf, row, col, fr, y0, y1); else *(GAS u32x4*)(uintptr_t)(Oh + o) = pack8(y0, y1); }
.LBB0_1856:
	global_load_dwordx2 v[56:57], v[182:183], off offset:1024
	s_nop 0
	global_load_dwordx4 v[44:47], v[158:159], off offset:256
	global_load_dwordx4 v[40:43], v[202:203], off offset:256
	s_waitcnt vmcnt(6)
	v_cvt_f32_u32_e32 v58, v96
	v_cvt_f32_i32_e32 v59, v97
	s_mov_b32 s12, 0x35000000
	s_mov_b32 s13, 0x33000000
	s_waitcnt vmcnt(5)
	v_lshlrev_b32_e32 v60, 16, v52
	v_pk_mul_f32 v[58:59], v[58:59], s[12:13]
	v_and_b32_e32 v61, 0xffff0000, v52
	v_fma_f32 v52, -v59, v59, v58
	v_max_f32_e32 v52, 0, v52
	v_add_f32_e32 v52, 0x3727c5ac, v52
	v_rsq_f32_e32 v52, v52
	v_fma_f32 v32, -v64, v59, v32
	v_fma_f32 v37, -v73, v59, v37
	v_fma_f32 v36, -v72, v59, v36
	v_fma_f32 v32, v32, v52, v68
	v_mul_f32_e32 v32, 0xbfb8aa3b, v32
	v_fma_f32 v37, v37, v52, v77
	v_exp_f32_e32 v32, v32
	v_mul_f32_e32 v37, 0xbfb8aa3b, v37
	v_exp_f32_e32 v37, v37
	v_fma_f32 v36, v36, v52, v76
	v_mul_f32_e32 v36, 0xbfb8aa3b, v36
	v_exp_f32_e32 v36, v36
	v_add_f32_e32 v32, 1.0, v32
	v_rcp_f32_e32 v98, v32
	v_add_f32_e32 v32, 1.0, v37
	v_fma_f32 v34, -v66, v59, v34
	v_rcp_f32_e32 v37, v32
	v_fma_f32 v32, -v65, v59, v33
	v_fma_f32 v34, v34, v52, v70
	v_fma_f32 v39, -v75, v59, v39
	v_fma_f32 v32, v32, v52, v69
	v_mul_f32_e32 v34, 0xbfb8aa3b, v34
	v_fma_f32 v39, v39, v52, v79
	v_add_f32_e32 v36, 1.0, v36
	v_mul_f32_e32 v32, 0xbfb8aa3b, v32
	v_exp_f32_e32 v34, v34
	v_mul_f32_e32 v39, 0xbfb8aa3b, v39
	v_rcp_f32_e32 v36, v36
	s_waitcnt vmcnt(4)
	v_lshlrev_b32_e32 v100, 16, v48
	v_and_b32_e32 v101, 0xffff0000, v48
	v_exp_f32_e32 v48, v32
	v_fma_f32 v38, -v74, v59, v38
	v_exp_f32_e32 v39, v39
	v_lshlrev_b32_e32 v58, 16, v53
	v_and_b32_e32 v53, 0xffff0000, v53
	v_sub_f32_e32 v61, v61, v59
	v_sub_f32_e32 v60, v60, v59
	v_fma_f32 v38, v38, v52, v78
	v_pk_mul_f32 v[60:61], v[60:61], v[52:53] op_sel_hi:[1,0]
	v_mul_f32_e32 v38, 0xbfb8aa3b, v38
	v_pk_fma_f32 v[32:33], v[88:89], v[60:61], v[92:93]
	v_exp_f32_e32 v38, v38
	v_add_f32_e32 v34, 1.0, v34
	v_pk_fma_f32 v[32:33], v[36:37], v[100:101], v[32:33]
	v_add_f32_e32 v36, 1.0, v48
	v_rcp_f32_e32 v48, v34
	v_add_f32_e32 v34, 1.0, v39
	v_rcp_f32_e32 v39, v34
	v_fma_f32 v34, -v67, v59, v35
	v_fma_f32 v34, v34, v52, v71
	v_add_f32_e32 v38, 1.0, v38
	v_mul_f32_e32 v34, 0xbfb8aa3b, v34
	v_rcp_f32_e32 v99, v36
	v_lshlrev_b32_e32 v36, 16, v50
	v_and_b32_e32 v37, 0xffff0000, v50
	v_rcp_f32_e32 v38, v38
	v_exp_f32_e32 v50, v34
	v_lshlrev_b32_e32 v96, 16, v54
	v_and_b32_e32 v97, 0xffff0000, v54
	v_lshlrev_b32_e32 v62, 16, v55
	v_and_b32_e32 v63, 0xffff0000, v55
	v_sub_f32_e32 v55, v53, v59
	v_sub_f32_e32 v54, v58, v59
	v_pk_mul_f32 v[54:55], v[54:55], v[52:53] op_sel_hi:[1,0]
	v_lshlrev_b32_e32 v34, 16, v49
	v_pk_fma_f32 v[54:55], v[90:91], v[54:55], v[94:95]
	v_and_b32_e32 v35, 0xffff0000, v49
	v_pk_fma_f32 v[34:35], v[38:39], v[34:35], v[54:55]
	v_add_f32_e32 v38, 1.0, v50
	v_rcp_f32_e32 v49, v38
	v_sub_f32_e32 v63, v63, v59
	v_sub_f32_e32 v62, v62, v59
	v_sub_f32_e32 v97, v97, v59
	v_sub_f32_e32 v96, v96, v59
	v_pk_mul_f32 v[96:97], v[96:97], v[52:53] op_sel_hi:[1,0]
	v_pk_mul_f32 v[62:63], v[62:63], v[52:53] op_sel_hi:[1,0]
	v_lshlrev_b32_e32 v38, 16, v51
	v_pk_fma_f32 v[60:61], v[82:83], v[62:63], v[86:87]
	v_pk_fma_f32 v[62:63], v[80:81], v[96:97], v[84:85]
	v_and_b32_e32 v39, 0xffff0000, v51
	v_pk_fma_f32 v[36:37], v[98:99], v[36:37], v[62:63]
	s_and_b64 vcc, exec, s[46:47]
	v_pk_fma_f32 v[38:39], v[48:49], v[38:39], v[60:61]
	s_cbranch_vccnz .LBB0_1905
	v_cndmask_b32_e64 v51, v35, v39, s[40:41]
	v_cndmask_b32_e64 v50, v34, v38, s[40:41]
	v_cndmask_b32_e64 v49, v33, v37, s[40:41]
	v_cndmask_b32_e64 v48, v32, v36, s[40:41]
	s_nop 1
	v_mov_b32_dpp v48, v48 row_ror:8 row_mask:0xf bank_mask:0xf
	s_nop 1
	v_mov_b32_dpp v49, v49 row_ror:8 row_mask:0xf bank_mask:0xf
	s_nop 1
	v_mov_b32_dpp v50, v50 row_ror:8 row_mask:0xf bank_mask:0xf
	s_nop 1
	v_mov_b32_dpp v51, v51 row_ror:8 row_mask:0xf bank_mask:0xf
	s_and_saveexec_b64 s[12:13], s[42:43]
	s_xor_b64 s[12:13], exec, s[12:13]
	v_mov_b64_e32 v[54:55], v[38:39]
	v_lshl_add_u64 v[58:59], v[160:161], 0, v[118:119]
	v_mov_b64_e32 v[52:53], v[36:37]
	s_andn2_saveexec_b64 s[12:13], s[12:13]
	v_or_b32_e32 v52, 56, v178
	v_ashrrev_i32_e32 v53, 31, v52
	v_lshlrev_b64 v[52:53], 11, v[52:53]
	v_lshl_add_u64 v[58:59], v[52:53], 0, v[114:115]
	v_mov_b64_e32 v[54:55], v[50:51]
	v_mov_b64_e32 v[52:53], v[48:49]
	v_mov_b64_e32 v[50:51], v[34:35]
	v_mov_b64_e32 v[48:49], v[32:33]
	s_or_b64 exec, exec, s[12:13]
	v_lshl_add_u64 v[62:63], v[180:181], 0, v[118:119]
	s_mov_b64 s[12:13], 0x14000
	v_lshl_add_u64 v[60:61], v[160:161], 0, v[114:115]
	v_lshl_add_u64 v[62:63], v[62:63], 0, s[12:13]
	v_cndmask_b32_e64 v61, v63, v61, s[40:41]
	v_cndmask_b32_e64 v60, v62, v60, s[40:41]
	v_lshl_add_u64 v[60:61], v[60:61], 2, s[4:5]
	global_store_dwordx4 v[60:61], v[48:51], off nt
	s_nop 1
	v_lshl_add_u64 v[48:49], v[58:59], 2, s[4:5]
	global_store_dwordx4 v[48:49], v[52:55], off nt
	s_branch .LBB0_1863

; #define GAS __attribute__((address_space(1)))
; __device__ __forceinline__ u32x4 pack8(f32x4 a, f32x4 b) { u32x4 w; w.x = cvt_pk_bf16(a[0], a[1]); w.y = cvt_pk_bf16(a[2], a[3]); w.z = cvt_pk_bf16(b[0], b[1]); w.w = cvt_pk_bf16(b[2], b[3]); return w; }
; __device__ __forceinline__ float bf_lo(unsigned w) { return __uint_as_float(w << 16); }
; __device__ __forceinline__ float bf_hi(unsigned w) { return __uint_as_float(w & 0xffff0000u); }
; __device__ __forceinline__ void st_rows_f32(float* Y, int row, int col, int fr, f32x4 y0, f32x4 y1) {
;     const bool lo8 = fr < 8; const f32x4 snd = lo8 ? y1 : y0, rcv = dpp_ror8(snd);
;     const size_t a1 = lo8 ? (size_t)row * DM + col : (size_t)(row - 8) * DM + col + 4, a2 = lo8 ? (size_t)(row + 8) * DM + col : (size_t)row * DM + col + 4;
;     __builtin_nontemporal_store(lo8 ? y0 : rcv, (GAS f32x4*)(uintptr_t)(Y + a1)); __builtin_nontemporal_store(lo8 ? rcv : y1, (GAS f32x4*)(uintptr_t)(Y + a2));
; }
;     __device__ __forceinline__ void operator()(EP_ARGS) const {
;     ...
;             PLE_LD(0, 0);
; #pragma unroll
;             for (int k = 0; k < 8; ++k) { const int ai = k >> 2, m = k & 3;
;                 if (k < 7) PLE_LD(k + 1, (k + 1) & 1);
;                 __builtin_amdgcn_sched_barrier(0);
;                 { const int row = EP_ROW(ai, m); float mu, rstd; ln_unpack(tq[k & 1], mu, rstd); const size_t o = (size_t)row * DM + col;
;                     const u32x4 w_ = iw[k & 1], pw = pq[k & 1]; const f32x4 r0 = {bf_lo(w_.x), bf_hi(w_.x), bf_lo(w_.y), bf_hi(w_.y)}, r1 = {bf_lo(w_.z), bf_hi(w_.z), bf_lo(w_.w), bf_hi(w_.w)};
;                     const f32x4 x0 = (r0 - mu) * rstd * g0 + b0, x1 = (r1 - mu) * rstd * g1 + b1;
;                     const f32x4 t0 = (acc[ai][bj][m][0] - c0 * mu) * rstd + w0, t1 = (acc[ai][bj][m][1] - c1 * mu) * rstd + w1;
;                     const f32x4 p0 = {bf_lo(pw.x), bf_hi(pw.x), bf_lo(pw.y), bf_hi(pw.y)}, p1 = {bf_lo(pw.z), bf_hi(pw.z), bf_lo(pw.w), bf_hi(pw.w)};
;                     f32x4 y0, y1;
; #pragma unroll
;                     for (int j = 0; j < 4; ++j) { y0[j] = x0[j] + sigmoidf_(t0[j]) * p0[j]; y1[j] = x1[j] + sigmoidf_(t1[j]) * p1[j]; }
;                     if (Xf) st_rows_f32(Xf, row, col, fr, y0, y1); else *(GAS u32x4*)(uintptr_t)(Oh + o) = pack8(y0, y1); }
.LBB0_1863:
	global_load_dwordx2 v[48:49], v[144:145], off offset:128
	s_nop 0
	global_load_dwordx4 v[36:39], v[150:151], off offset:256
	global_load_dwordx4 v[32:35], v[204:205], off offset:256
	s_waitcnt vmcnt(6)
	v_cvt_f32_u32_e32 v50, v56
	v_cvt_f32_i32_e32 v51, v57
	s_mov_b32 s12, 0x35000000
	s_mov_b32 s13, 0x33000000
	s_waitcnt vmcnt(5)
	v_lshlrev_b32_e32 v52, 16, v44
	v_pk_mul_f32 v[50:51], v[50:51], s[12:13]
	v_and_b32_e32 v53, 0xffff0000, v44
	v_fma_f32 v44, -v51, v51, v50
	v_max_f32_e32 v44, 0, v44
	v_add_f32_e32 v44, 0x3727c5ac, v44
	v_rsq_f32_e32 v44, v44
	v_fma_f32 v24, -v64, v51, v24
	v_fma_f32 v29, -v73, v51, v29
	v_fma_f32 v28, -v72, v51, v28
	v_fma_f32 v24, v24, v44, v68
	v_mul_f32_e32 v24, 0xbfb8aa3b, v24
	v_fma_f32 v29, v29, v44, v77
	v_exp_f32_e32 v24, v24
	v_mul_f32_e32 v29, 0xbfb8aa3b, v29
	v_exp_f32_e32 v29, v29
	v_fma_f32 v28, v28, v44, v76
	v_mul_f32_e32 v28, 0xbfb8aa3b, v28
	v_exp_f32_e32 v28, v28
	v_add_f32_e32 v24, 1.0, v24
	v_rcp_f32_e32 v58, v24
	v_add_f32_e32 v24, 1.0, v29
	v_fma_f32 v26, -v66, v51, v26
	v_rcp_f32_e32 v29, v24
	v_fma_f32 v24, -v65, v51, v25
	v_fma_f32 v26, v26, v44, v70
	v_fma_f32 v31, -v75, v51, v31
	v_fma_f32 v24, v24, v44, v69
	v_mul_f32_e32 v26, 0xbfb8aa3b, v26
	v_fma_f32 v31, v31, v44, v79
	v_add_f32_e32 v28, 1.0, v28
	v_mul_f32_e32 v24, 0xbfb8aa3b, v24
	v_exp_f32_e32 v26, v26
	v_mul_f32_e32 v31, 0xbfb8aa3b, v31
	v_rcp_f32_e32 v28, v28
	s_waitcnt vmcnt(4)
	v_lshlrev_b32_e32 v60, 16, v40
	v_and_b32_e32 v61, 0xffff0000, v40
	v_exp_f32_e32 v40, v24
	v_fma_f32 v30, -v74, v51, v30
	v_exp_f32_e32 v31, v31
	v_lshlrev_b32_e32 v50, 16, v45
	v_and_b32_e32 v45, 0xffff0000, v45
	v_sub_f32_e32 v53, v53, v51
	v_sub_f32_e32 v52, v52, v51
	v_fma_f32 v30, v30, v44, v78
	v_pk_mul_f32 v[52:53], v[52:53], v[44:45] op_sel_hi:[1,0]
	v_mul_f32_e32 v30, 0xbfb8aa3b, v30
	v_pk_fma_f32 v[24:25], v[88:89], v[52:53], v[92:93]
	v_exp_f32_e32 v30, v30
	v_add_f32_e32 v26, 1.0, v26
	v_pk_fma_f32 v[24:25], v[28:29], v[60:61], v[24:25]
	v_add_f32_e32 v28, 1.0, v40
	v_rcp_f32_e32 v40, v26
	v_add_f32_e32 v26, 1.0, v31
	v_rcp_f32_e32 v31, v26
	v_fma_f32 v26, -v67, v51, v27
	v_fma_f32 v26, v26, v44, v71
	v_add_f32_e32 v30, 1.0, v30
	v_mul_f32_e32 v26, 0xbfb8aa3b, v26
	v_rcp_f32_e32 v59, v28
	v_lshlrev_b32_e32 v28, 16, v42
	v_and_b32_e32 v29, 0xffff0000, v42
	v_rcp_f32_e32 v30, v30
	v_exp_f32_e32 v42, v26
	v_lshlrev_b32_e32 v56, 16, v46
	v_and_b32_e32 v57, 0xffff0000, v46
	v_lshlrev_b32_e32 v54, 16, v47
	v_and_b32_e32 v55, 0xffff0000, v47
	v_sub_f32_e32 v47, v45, v51
	v_sub_f32_e32 v46, v50, v51
	v_pk_mul_f32 v[46:47], v[46:47], v[44:45] op_sel_hi:[1,0]
	v_lshlrev_b32_e32 v26, 16, v41
	v_pk_fma_f32 v[46:47], v[90:91], v[46:47], v[94:95]
	v_and_b32_e32 v27, 0xffff0000, v41
	v_pk_fma_f32 v[26:27], v[30:31], v[26:27], v[46:47]
	v_add_f32_e32 v30, 1.0, v42
	v_rcp_f32_e32 v41, v30
	v_sub_f32_e32 v55, v55, v51
	v_sub_f32_e32 v54, v54, v51
	v_sub_f32_e32 v57, v57, v51
	v_sub_f32_e32 v56, v56, v51
	v_pk_mul_f32 v[56:57], v[56:57], v[44:45] op_sel_hi:[1,0]
	v_pk_mul_f32 v[54:55], v[54:55], v[44:45] op_sel_hi:[1,0]
	v_lshlrev_b32_e32 v30, 16, v43
	v_pk_fma_f32 v[52:53], v[82:83], v[54:55], v[86:87]
	v_pk_fma_f32 v[54:55], v[80:81], v[56:57], v[84:85]
	v_and_b32_e32 v31, 0xffff0000, v43
	v_pk_fma_f32 v[28:29], v[58:59], v[28:29], v[54:55]
	s_and_b64 vcc, exec, s[46:47]
	v_pk_fma_f32 v[30:31], v[40:41], v[30:31], v[52:53]
	s_cbranch_vccnz .LBB0_1906
	v_cndmask_b32_e64 v43, v27, v31, s[40:41]
	v_cndmask_b32_e64 v42, v26, v30, s[40:41]
	v_cndmask_b32_e64 v41, v25, v29, s[40:41]
	v_cndmask_b32_e64 v40, v24, v28, s[40:41]
	s_nop 1
	v_mov_b32_dpp v40, v40 row_ror:8 row_mask:0xf bank_mask:0xf
	s_nop 1
	v_mov_b32_dpp v41, v41 row_ror:8 row_mask:0xf bank_mask:0xf
	s_nop 1
	v_mov_b32_dpp v42, v42 row_ror:8 row_mask:0xf bank_mask:0xf
	s_nop 1
	v_mov_b32_dpp v43, v43 row_ror:8 row_mask:0xf bank_mask:0xf
	s_and_saveexec_b64 s[12:13], s[42:43]
	s_xor_b64 s[12:13], exec, s[12:13]
	v_mov_b64_e32 v[46:47], v[30:31]
	v_lshl_add_u64 v[50:51], v[154:155], 0, v[118:119]
	v_mov_b64_e32 v[44:45], v[28:29]
	s_andn2_saveexec_b64 s[12:13], s[12:13]
	v_or_b32_e32 v44, 8, v152
	v_ashrrev_i32_e32 v45, 31, v44
	v_lshlrev_b64 v[44:45], 11, v[44:45]
	v_lshl_add_u64 v[50:51], v[44:45], 0, v[114:115]
	v_mov_b64_e32 v[46:47], v[42:43]
	v_mov_b64_e32 v[44:45], v[40:41]
	v_mov_b64_e32 v[42:43], v[26:27]
	v_mov_b64_e32 v[40:41], v[24:25]
	s_or_b64 exec, exec, s[12:13]
	v_add_u32_e32 v54, 0x78, v178
	v_ashrrev_i32_e32 v55, 31, v54
	v_lshlrev_b64 v[54:55], 11, v[54:55]
	v_lshl_add_u64 v[52:53], v[154:155], 0, v[114:115]
	v_lshl_add_u64 v[54:55], v[54:55], 0, v[118:119]
	v_cndmask_b32_e64 v53, v55, v53, s[40:41]
	v_cndmask_b32_e64 v52, v54, v52, s[40:41]
	v_lshl_add_u64 v[52:53], v[52:53], 2, s[4:5]
	global_store_dwordx4 v[52:53], v[40:43], off nt
	s_nop 1
	v_lshl_add_u64 v[40:41], v[50:51], 2, s[4:5]
	global_store_dwordx4 v[40:41], v[44:47], off nt
	s_branch .LBB0_1870

; #define GAS __attribute__((address_space(1)))
; __device__ __forceinline__ u32x4 pack8(f32x4 a, f32x4 b) { u32x4 w; w.x = cvt_pk_bf16(a[0], a[1]); w.y = cvt_pk_bf16(a[2], a[3]); w.z = cvt_pk_bf16(b[0], b[1]); w.w = cvt_pk_bf16(b[2], b[3]); return w; }
; __device__ __forceinline__ float bf_lo(unsigned w) { return __uint_as_float(w << 16); }
; __device__ __forceinline__ float bf_hi(unsigned w) { return __uint_as_float(w & 0xffff0000u); }
; __device__ __forceinline__ void st_rows_f32(float* Y, int row, int col, int fr, f32x4 y0, f32x4 y1) {
;     const bool lo8 = fr < 8; const f32x4 snd = lo8 ? y1 : y0, rcv = dpp_ror8(snd);
;     const size_t a1 = lo8 ? (size_t)row * DM + col : (size_t)(row - 8) * DM + col + 4, a2 = lo8 ? (size_t)(row + 8) * DM + col : (size_t)row * DM + col + 4;
;     __builtin_nontemporal_store(lo8 ? y0 : rcv, (GAS f32x4*)(uintptr_t)(Y + a1)); __builtin_nontemporal_store(lo8 ? rcv : y1, (GAS f32x4*)(uintptr_t)(Y + a2));
; }
;     __device__ __forceinline__ void operator()(EP_ARGS) const {
;     ...
;             PLE_LD(0, 0);
; #pragma unroll
;             for (int k = 0; k < 8; ++k) { const int ai = k >> 2, m = k & 3;
;                 if (k < 7) PLE_LD(k + 1, (k + 1) & 1);
;                 __builtin_amdgcn_sched_barrier(0);
;                 { const int row = EP_ROW(ai, m); float mu, rstd; ln_unpack(tq[k & 1], mu, rstd); const size_t o = (size_t)row * DM + col;
;                     const u32x4 w_ = iw[k & 1], pw = pq[k & 1]; const f32x4 r0 = {bf_lo(w_.x), bf_hi(w_.x), bf_lo(w_.y), bf_hi(w_.y)}, r1 = {bf_lo(w_.z), bf_hi(w_.z), bf_lo(w_.w), bf_hi(w_.w)};
;                     const f32x4 x0 = (r0 - mu) * rstd * g0 + b0, x1 = (r1 - mu) * rstd * g1 + b1;
;                     const f32x4 t0 = (acc[ai][bj][m][0] - c0 * mu) * rstd + w0, t1 = (acc[ai][bj][m][1] - c1 * mu) * rstd + w1;
;                     const f32x4 p0 = {bf_lo(pw.x), bf_hi(pw.x), bf_lo(pw.y), bf_hi(pw.y)}, p1 = {bf_lo(pw.z), bf_hi(pw.z), bf_lo(pw.w), bf_hi(pw.w)};
;                     f32x4 y0, y1;
; #pragma unroll
;                     for (int j = 0; j < 4; ++j) { y0[j] = x0[j] + sigmoidf_(t0[j]) * p0[j]; y1[j] = x1[j] + sigmoidf_(t1[j]) * p1[j]; }
;                     if (Xf) st_rows_f32(Xf, row, col, fr, y0, y1); else *(GAS u32x4*)(uintptr_t)(Oh + o) = pack8(y0, y1); }
.LBB0_1870:
	global_load_dwordx2 v[40:41], v[144:145], off offset:256
	s_nop 0
	global_load_dwordx4 v[28:31], v[140:141], off offset:256
	global_load_dwordx4 v[24:27], v[142:143], off offset:256
	s_waitcnt vmcnt(6)
	v_cvt_f32_u32_e32 v42, v48
	v_cvt_f32_i32_e32 v43, v49
	s_mov_b32 s12, 0x35000000
	s_mov_b32 s13, 0x33000000
	s_waitcnt vmcnt(5)
	v_lshlrev_b32_e32 v44, 16, v36
	v_pk_mul_f32 v[42:43], v[42:43], s[12:13]
	v_and_b32_e32 v45, 0xffff0000, v36
	v_fma_f32 v36, -v43, v43, v42
	v_max_f32_e32 v36, 0, v36
	v_add_f32_e32 v36, 0x3727c5ac, v36
	v_rsq_f32_e32 v36, v36
	v_fma_f32 v16, -v64, v43, v16
	v_fma_f32 v21, -v73, v43, v21
	v_fma_f32 v20, -v72, v43, v20
	v_fma_f32 v16, v16, v36, v68
	v_mul_f32_e32 v16, 0xbfb8aa3b, v16
	v_fma_f32 v21, v21, v36, v77
	v_exp_f32_e32 v16, v16
	v_mul_f32_e32 v21, 0xbfb8aa3b, v21
	v_exp_f32_e32 v21, v21
	v_fma_f32 v20, v20, v36, v76
	v_mul_f32_e32 v20, 0xbfb8aa3b, v20
	v_exp_f32_e32 v20, v20
	v_add_f32_e32 v16, 1.0, v16
	v_rcp_f32_e32 v50, v16
	v_add_f32_e32 v16, 1.0, v21
	v_fma_f32 v18, -v66, v43, v18
	v_rcp_f32_e32 v21, v16
	v_fma_f32 v16, -v65, v43, v17
	v_fma_f32 v18, v18, v36, v70
	v_fma_f32 v23, -v75, v43, v23
	v_fma_f32 v16, v16, v36, v69
	v_mul_f32_e32 v18, 0xbfb8aa3b, v18
	v_fma_f32 v23, v23, v36, v79
	v_add_f32_e32 v20, 1.0, v20
	v_mul_f32_e32 v16, 0xbfb8aa3b, v16
	v_exp_f32_e32 v18, v18
	v_mul_f32_e32 v23, 0xbfb8aa3b, v23
	v_rcp_f32_e32 v20, v20
	s_waitcnt vmcnt(4)
	v_lshlrev_b32_e32 v52, 16, v32
	v_and_b32_e32 v53, 0xffff0000, v32
	v_exp_f32_e32 v32, v16
	v_fma_f32 v22, -v74, v43, v22
	v_exp_f32_e32 v23, v23
	v_lshlrev_b32_e32 v42, 16, v37
	v_and_b32_e32 v37, 0xffff0000, v37
	v_sub_f32_e32 v45, v45, v43
	v_sub_f32_e32 v44, v44, v43
	v_fma_f32 v22, v22, v36, v78
	v_pk_mul_f32 v[44:45], v[44:45], v[36:37] op_sel_hi:[1,0]
	v_mul_f32_e32 v22, 0xbfb8aa3b, v22
	v_pk_fma_f32 v[16:17], v[88:89], v[44:45], v[92:93]
	v_exp_f32_e32 v22, v22
	v_add_f32_e32 v18, 1.0, v18
	v_pk_fma_f32 v[16:17], v[20:21], v[52:53], v[16:17]
	v_add_f32_e32 v20, 1.0, v32
	v_rcp_f32_e32 v32, v18
	v_add_f32_e32 v18, 1.0, v23
	v_rcp_f32_e32 v23, v18
	v_fma_f32 v18, -v67, v43, v19
	v_fma_f32 v18, v18, v36, v71
	v_add_f32_e32 v22, 1.0, v22
	v_mul_f32_e32 v18, 0xbfb8aa3b, v18
	v_rcp_f32_e32 v51, v20
	v_lshlrev_b32_e32 v20, 16, v34
	v_and_b32_e32 v21, 0xffff0000, v34
	v_rcp_f32_e32 v22, v22
	v_exp_f32_e32 v34, v18
	v_lshlrev_b32_e32 v48, 16, v38
	v_and_b32_e32 v49, 0xffff0000, v38
	v_lshlrev_b32_e32 v46, 16, v39
	v_and_b32_e32 v47, 0xffff0000, v39
	v_sub_f32_e32 v39, v37, v43
	v_sub_f32_e32 v38, v42, v43
	v_pk_mul_f32 v[38:39], v[38:39], v[36:37] op_sel_hi:[1,0]
	v_lshlrev_b32_e32 v18, 16, v33
	v_pk_fma_f32 v[38:39], v[90:91], v[38:39], v[94:95]
	v_and_b32_e32 v19, 0xffff0000, v33
	v_pk_fma_f32 v[18:19], v[22:23], v[18:19], v[38:39]
	v_add_f32_e32 v22, 1.0, v34
	v_rcp_f32_e32 v33, v22
	v_sub_f32_e32 v47, v47, v43
	v_sub_f32_e32 v46, v46, v43
	v_sub_f32_e32 v49, v49, v43
	v_sub_f32_e32 v48, v48, v43
	v_pk_mul_f32 v[48:49], v[48:49], v[36:37] op_sel_hi:[1,0]
	v_pk_mul_f32 v[46:47], v[46:47], v[36:37] op_sel_hi:[1,0]
	v_lshlrev_b32_e32 v22, 16, v35
	v_pk_fma_f32 v[44:45], v[82:83], v[46:47], v[86:87]
	v_pk_fma_f32 v[46:47], v[80:81], v[48:49], v[84:85]
	v_and_b32_e32 v23, 0xffff0000, v35
	v_pk_fma_f32 v[20:21], v[50:51], v[20:21], v[46:47]
	s_and_b64 vcc, exec, s[46:47]
	v_pk_fma_f32 v[22:23], v[32:33], v[22:23], v[44:45]
	s_cbranch_vccnz .LBB0_1907
	v_cndmask_b32_e64 v35, v19, v23, s[40:41]
	v_cndmask_b32_e64 v34, v18, v22, s[40:41]
	v_cndmask_b32_e64 v33, v17, v21, s[40:41]
	v_cndmask_b32_e64 v32, v16, v20, s[40:41]
	s_nop 1
	v_mov_b32_dpp v32, v32 row_ror:8 row_mask:0xf bank_mask:0xf
	s_nop 1
	v_mov_b32_dpp v33, v33 row_ror:8 row_mask:0xf bank_mask:0xf
	s_nop 1
	v_mov_b32_dpp v34, v34 row_ror:8 row_mask:0xf bank_mask:0xf
	s_nop 1
	v_mov_b32_dpp v35, v35 row_ror:8 row_mask:0xf bank_mask:0xf
	s_and_saveexec_b64 s[12:13], s[42:43]
	s_xor_b64 s[12:13], exec, s[12:13]
	v_mov_b64_e32 v[38:39], v[22:23]
	v_lshl_add_u64 v[42:43], v[146:147], 0, v[118:119]
	v_mov_b64_e32 v[36:37], v[20:21]
	s_andn2_saveexec_b64 s[12:13], s[12:13]
	v_or_b32_e32 v36, 24, v152
	v_ashrrev_i32_e32 v37, 31, v36
	v_lshlrev_b64 v[36:37], 11, v[36:37]
	v_lshl_add_u64 v[42:43], v[36:37], 0, v[114:115]
	v_mov_b64_e32 v[38:39], v[34:35]
	v_mov_b64_e32 v[36:37], v[32:33]
	v_mov_b64_e32 v[34:35], v[18:19]
	v_mov_b64_e32 v[32:33], v[16:17]
	s_or_b64 exec, exec, s[12:13]
	v_add_u32_e32 v46, 0x88, v178
	v_ashrrev_i32_e32 v47, 31, v46
	v_lshlrev_b64 v[46:47], 11, v[46:47]
	v_lshl_add_u64 v[44:45], v[146:147], 0, v[114:115]
	v_lshl_add_u64 v[46:47], v[46:47], 0, v[118:119]
	v_cndmask_b32_e64 v45, v47, v45, s[40:41]
	v_cndmask_b32_e64 v44, v46, v44, s[40:41]
	v_lshl_add_u64 v[44:45], v[44:45], 2, s[4:5]
	global_store_dwordx4 v[44:45], v[32:35], off nt
	s_nop 1
	v_lshl_add_u64 v[32:33], v[42:43], 2, s[4:5]
	global_store_dwordx4 v[32:33], v[36:39], off nt
	s_branch .LBB0_1877

; #define GAS __attribute__((address_space(1)))
; __device__ __forceinline__ u32x4 pack8(f32x4 a, f32x4 b) { u32x4 w; w.x = cvt_pk_bf16(a[0], a[1]); w.y = cvt_pk_bf16(a[2], a[3]); w.z = cvt_pk_bf16(b[0], b[1]); w.w = cvt_pk_bf16(b[2], b[3]); return w; }
; __device__ __forceinline__ float bf_lo(unsigned w) { return __uint_as_float(w << 16); }
; __device__ __forceinline__ float bf_hi(unsigned w) { return __uint_as_float(w & 0xffff0000u); }
; __device__ __forceinline__ void st_rows_f32(float* Y, int row, int col, int fr, f32x4 y0, f32x4 y1) {
;     const bool lo8 = fr < 8; const f32x4 snd = lo8 ? y1 : y0, rcv = dpp_ror8(snd);
;     const size_t a1 = lo8 ? (size_t)row * DM + col : (size_t)(row - 8) * DM + col + 4, a2 = lo8 ? (size_t)(row + 8) * DM + col : (size_t)row * DM + col + 4;
;     __builtin_nontemporal_store(lo8 ? y0 : rcv, (GAS f32x4*)(uintptr_t)(Y + a1)); __builtin_nontemporal_store(lo8 ? rcv : y1, (GAS f32x4*)(uintptr_t)(Y + a2));
; }
;     __device__ __forceinline__ void operator()(EP_ARGS) const {
;     ...
;             PLE_LD(0, 0);
; #pragma unroll
;             for (int k = 0; k < 8; ++k) { const int ai = k >> 2, m = k & 3;
;                 if (k < 7) PLE_LD(k + 1, (k + 1) & 1);
;                 __builtin_amdgcn_sched_barrier(0);
;                 { const int row = EP_ROW(ai, m); float mu, rstd; ln_unpack(tq[k & 1], mu, rstd); const size_t o = (size_t)row * DM + col;
;                     const u32x4 w_ = iw[k & 1], pw = pq[k & 1]; const f32x4 r0 = {bf_lo(w_.x), bf_hi(w_.x), bf_lo(w_.y), bf_hi(w_.y)}, r1 = {bf_lo(w_.z), bf_hi(w_.z), bf_lo(w_.w), bf_hi(w_.w)};
;                     const f32x4 x0 = (r0 - mu) * rstd * g0 + b0, x1 = (r1 - mu) * rstd * g1 + b1;
;                     const f32x4 t0 = (acc[ai][bj][m][0] - c0 * mu) * rstd + w0, t1 = (acc[ai][bj][m][1] - c1 * mu) * rstd + w1;
;                     const f32x4 p0 = {bf_lo(pw.x), bf_hi(pw.x), bf_lo(pw.y), bf_hi(pw.y)}, p1 = {bf_lo(pw.z), bf_hi(pw.z), bf_lo(pw.w), bf_hi(pw.w)};
;                     f32x4 y0, y1;
; #pragma unroll
;                     for (int j = 0; j < 4; ++j) { y0[j] = x0[j] + sigmoidf_(t0[j]) * p0[j]; y1[j] = x1[j] + sigmoidf_(t1[j]) * p1[j]; }
;                     if (Xf) st_rows_f32(Xf, row, col, fr, y0, y1); else *(GAS u32x4*)(uintptr_t)(Oh + o) = pack8(y0, y1); }
.LBB0_1877:
	global_load_dwordx2 v[32:33], v[144:145], off offset:384
	s_nop 0
	global_load_dwordx4 v[20:23], v[132:133], off offset:256
	global_load_dwordx4 v[16:19], v[134:135], off offset:256
	s_waitcnt vmcnt(6)
	v_cvt_f32_u32_e32 v34, v40
	v_cvt_f32_i32_e32 v35, v41
	s_mov_b32 s12, 0x35000000
	s_mov_b32 s13, 0x33000000
	s_waitcnt vmcnt(5)
	v_lshlrev_b32_e32 v36, 16, v28
	v_pk_mul_f32 v[34:35], v[34:35], s[12:13]
	v_and_b32_e32 v37, 0xffff0000, v28
	v_fma_f32 v28, -v35, v35, v34
	v_max_f32_e32 v28, 0, v28
	v_add_f32_e32 v28, 0x3727c5ac, v28
	v_rsq_f32_e32 v28, v28
	v_fma_f32 v8, -v64, v35, v8
	v_fma_f32 v13, -v73, v35, v13
	v_fma_f32 v12, -v72, v35, v12
	v_fma_f32 v8, v8, v28, v68
	v_mul_f32_e32 v8, 0xbfb8aa3b, v8
	v_fma_f32 v13, v13, v28, v77
	v_exp_f32_e32 v8, v8
	v_mul_f32_e32 v13, 0xbfb8aa3b, v13
	v_exp_f32_e32 v13, v13
	v_fma_f32 v12, v12, v28, v76
	v_mul_f32_e32 v12, 0xbfb8aa3b, v12
	v_exp_f32_e32 v12, v12
	v_add_f32_e32 v8, 1.0, v8
	v_rcp_f32_e32 v42, v8
	v_add_f32_e32 v8, 1.0, v13
	v_fma_f32 v10, -v66, v35, v10
	v_rcp_f32_e32 v13, v8
	v_fma_f32 v8, -v65, v35, v9
	v_fma_f32 v10, v10, v28, v70
	v_fma_f32 v15, -v75, v35, v15
	v_fma_f32 v8, v8, v28, v69
	v_mul_f32_e32 v10, 0xbfb8aa3b, v10
	v_fma_f32 v15, v15, v28, v79
	v_add_f32_e32 v12, 1.0, v12
	v_mul_f32_e32 v8, 0xbfb8aa3b, v8
	v_exp_f32_e32 v10, v10
	v_mul_f32_e32 v15, 0xbfb8aa3b, v15
	v_rcp_f32_e32 v12, v12
	s_waitcnt vmcnt(4)
	v_lshlrev_b32_e32 v44, 16, v24
	v_and_b32_e32 v45, 0xffff0000, v24
	v_exp_f32_e32 v24, v8
	v_fma_f32 v14, -v74, v35, v14
	v_exp_f32_e32 v15, v15
	v_lshlrev_b32_e32 v34, 16, v29
	v_and_b32_e32 v29, 0xffff0000, v29
	v_sub_f32_e32 v37, v37, v35
	v_sub_f32_e32 v36, v36, v35
	v_fma_f32 v14, v14, v28, v78
	v_pk_mul_f32 v[36:37], v[36:37], v[28:29] op_sel_hi:[1,0]
	v_mul_f32_e32 v14, 0xbfb8aa3b, v14
	v_pk_fma_f32 v[8:9], v[88:89], v[36:37], v[92:93]
	v_exp_f32_e32 v14, v14
	v_add_f32_e32 v10, 1.0, v10
	v_pk_fma_f32 v[8:9], v[12:13], v[44:45], v[8:9]
	v_add_f32_e32 v12, 1.0, v24
	v_rcp_f32_e32 v24, v10
	v_add_f32_e32 v10, 1.0, v15
	v_rcp_f32_e32 v15, v10
	v_fma_f32 v10, -v67, v35, v11
	v_fma_f32 v10, v10, v28, v71
	v_add_f32_e32 v14, 1.0, v14
	v_mul_f32_e32 v10, 0xbfb8aa3b, v10
	v_rcp_f32_e32 v43, v12
	v_lshlrev_b32_e32 v12, 16, v26
	v_and_b32_e32 v13, 0xffff0000, v26
	v_rcp_f32_e32 v14, v14
	v_exp_f32_e32 v26, v10
	v_lshlrev_b32_e32 v40, 16, v30
	v_and_b32_e32 v41, 0xffff0000, v30
	v_lshlrev_b32_e32 v38, 16, v31
	v_and_b32_e32 v39, 0xffff0000, v31
	v_sub_f32_e32 v31, v29, v35
	v_sub_f32_e32 v30, v34, v35
	v_pk_mul_f32 v[30:31], v[30:31], v[28:29] op_sel_hi:[1,0]
	v_lshlrev_b32_e32 v10, 16, v25
	v_pk_fma_f32 v[30:31], v[90:91], v[30:31], v[94:95]
	v_and_b32_e32 v11, 0xffff0000, v25
	v_pk_fma_f32 v[10:11], v[14:15], v[10:11], v[30:31]
	v_add_f32_e32 v14, 1.0, v26
	v_rcp_f32_e32 v25, v14
	v_sub_f32_e32 v39, v39, v35
	v_sub_f32_e32 v38, v38, v35
	v_sub_f32_e32 v41, v41, v35
	v_sub_f32_e32 v40, v40, v35
	v_pk_mul_f32 v[40:41], v[40:41], v[28:29] op_sel_hi:[1,0]
	v_pk_mul_f32 v[38:39], v[38:39], v[28:29] op_sel_hi:[1,0]
	v_lshlrev_b32_e32 v14, 16, v27
	v_pk_fma_f32 v[36:37], v[82:83], v[38:39], v[86:87]
	v_pk_fma_f32 v[38:39], v[80:81], v[40:41], v[84:85]
	v_and_b32_e32 v15, 0xffff0000, v27
	v_pk_fma_f32 v[12:13], v[42:43], v[12:13], v[38:39]
	s_and_b64 vcc, exec, s[46:47]
	v_pk_fma_f32 v[14:15], v[24:25], v[14:15], v[36:37]
	s_cbranch_vccnz .LBB0_1908
	v_cndmask_b32_e64 v27, v11, v15, s[40:41]
	v_cndmask_b32_e64 v26, v10, v14, s[40:41]
	v_cndmask_b32_e64 v25, v9, v13, s[40:41]
	v_cndmask_b32_e64 v24, v8, v12, s[40:41]
	s_nop 1
	v_mov_b32_dpp v24, v24 row_ror:8 row_mask:0xf bank_mask:0xf
	s_nop 1
	v_mov_b32_dpp v25, v25 row_ror:8 row_mask:0xf bank_mask:0xf
	s_nop 1
	v_mov_b32_dpp v26, v26 row_ror:8 row_mask:0xf bank_mask:0xf
	s_nop 1
	v_mov_b32_dpp v27, v27 row_ror:8 row_mask:0xf bank_mask:0xf
	s_and_saveexec_b64 s[12:13], s[42:43]
	s_xor_b64 s[12:13], exec, s[12:13]
	v_mov_b64_e32 v[30:31], v[14:15]
	v_lshl_add_u64 v[34:35], v[136:137], 0, v[118:119]
	v_mov_b64_e32 v[28:29], v[12:13]
	s_andn2_saveexec_b64 s[12:13], s[12:13]
	v_or_b32_e32 v28, 40, v152
	v_ashrrev_i32_e32 v29, 31, v28
	v_lshlrev_b64 v[28:29], 11, v[28:29]
	v_lshl_add_u64 v[34:35], v[28:29], 0, v[114:115]
	v_mov_b64_e32 v[30:31], v[26:27]
	v_mov_b64_e32 v[28:29], v[24:25]
	v_mov_b64_e32 v[26:27], v[10:11]
	v_mov_b64_e32 v[24:25], v[8:9]
	s_or_b64 exec, exec, s[12:13]
	v_add_u32_e32 v38, 0x98, v178
	v_ashrrev_i32_e32 v39, 31, v38
	v_lshlrev_b64 v[38:39], 11, v[38:39]
	v_lshl_add_u64 v[36:37], v[136:137], 0, v[114:115]
	v_lshl_add_u64 v[38:39], v[38:39], 0, v[118:119]
	v_cndmask_b32_e64 v37, v39, v37, s[40:41]
	v_cndmask_b32_e64 v36, v38, v36, s[40:41]
	v_lshl_add_u64 v[36:37], v[36:37], 2, s[4:5]
	global_store_dwordx4 v[36:37], v[24:27], off nt
	s_nop 1
	v_lshl_add_u64 v[24:25], v[34:35], 2, s[4:5]
	global_store_dwordx4 v[24:25], v[28:31], off nt
	s_branch .LBB0_1884

; #define GAS __attribute__((address_space(1)))
; __device__ __forceinline__ u32x4 pack8(f32x4 a, f32x4 b) { u32x4 w; w.x = cvt_pk_bf16(a[0], a[1]); w.y = cvt_pk_bf16(a[2], a[3]); w.z = cvt_pk_bf16(b[0], b[1]); w.w = cvt_pk_bf16(b[2], b[3]); return w; }
; __device__ __forceinline__ float bf_lo(unsigned w) { return __uint_as_float(w << 16); }
; __device__ __forceinline__ float bf_hi(unsigned w) { return __uint_as_float(w & 0xffff0000u); }
; __device__ __forceinline__ float sigmoidf_(float x) { return __builtin_amdgcn_rcpf(1.0f + __builtin_amdgcn_exp2f(-x * LOG2E)); }
; __device__ __forceinline__ f32x4 dpp_ror8(f32x4 v) { f32x4 r; r.x = dpp_ror8_1(v.x); r.y = dpp_ror8_1(v.y); r.z = dpp_ror8_1(v.z); r.w = dpp_ror8_1(v.w); return r; }
; __device__ __forceinline__ void st_rows_f32(float* Y, int row, int col, int fr, f32x4 y0, f32x4 y1) {
;     const bool lo8 = fr < 8; const f32x4 snd = lo8 ? y1 : y0, rcv = dpp_ror8(snd);
;     const size_t a1 = lo8 ? (size_t)row * DM + col : (size_t)(row - 8) * DM + col + 4, a2 = lo8 ? (size_t)(row + 8) * DM + col : (size_t)row * DM + col + 4;
;     __builtin_nontemporal_store(lo8 ? y0 : rcv, (GAS f32x4*)(uintptr_t)(Y + a1)); __builtin_nontemporal_store(lo8 ? rcv : y1, (GAS f32x4*)(uintptr_t)(Y + a2));
; }
;     __device__ __forceinline__ void operator()(EP_ARGS) const {
;     ...
;                 { const int row = EP_ROW(ai, m); float mu, rstd; ln_unpack(tq[k & 1], mu, rstd); const size_t o = (size_t)row * DM + col;
;                     const u32x4 w_ = iw[k & 1], pw = pq[k & 1]; const f32x4 r0 = {bf_lo(w_.x), bf_hi(w_.x), bf_lo(w_.y), bf_hi(w_.y)}, r1 = {bf_lo(w_.z), bf_hi(w_.z), bf_lo(w_.w), bf_hi(w_.w)};
;                     const f32x4 x0 = (r0 - mu) * rstd * g0 + b0, x1 = (r1 - mu) * rstd * g1 + b1;
;                     const f32x4 t0 = (acc[ai][bj][m][0] - c0 * mu) * rstd + w0, t1 = (acc[ai][bj][m][1] - c1 * mu) * rstd + w1;
;                     const f32x4 p0 = {bf_lo(pw.x), bf_hi(pw.x), bf_lo(pw.y), bf_hi(pw.y)}, p1 = {bf_lo(pw.z), bf_hi(pw.z), bf_lo(pw.w), bf_hi(pw.w)};
;                     f32x4 y0, y1;
; #pragma unroll
;                     for (int j = 0; j < 4; ++j) { y0[j] = x0[j] + sigmoidf_(t0[j]) * p0[j]; y1[j] = x1[j] + sigmoidf_(t1[j]) * p1[j]; }
;                     if (Xf) st_rows_f32(Xf, row, col, fr, y0, y1); else *(GAS u32x4*)(uintptr_t)(Oh + o) = pack8(y0, y1); }
.LBB0_1884:
	s_waitcnt vmcnt(3)
	s_nop 0
	v_cvt_f32_u32_e32 v8, v32
	v_cvt_f32_i32_e32 v9, v33
	s_mov_b32 s12, 0x35000000
	s_mov_b32 s13, 0x33000000
	s_waitcnt vmcnt(2)
	v_lshlrev_b32_e32 v12, 16, v20
	v_pk_mul_f32 v[8:9], v[8:9], s[12:13]
	v_and_b32_e32 v13, 0xffff0000, v20
	v_fma_f32 v8, -v9, v9, v8
	v_max_f32_e32 v8, 0, v8
	v_add_f32_e32 v8, 0x3727c5ac, v8
	v_rsq_f32_e32 v8, v8
	v_fma_f32 v0, -v64, v9, v0
	v_fma_f32 v5, -v73, v9, v5
	v_fma_f32 v4, -v72, v9, v4
	v_fma_f32 v0, v0, v8, v68
	v_mul_f32_e32 v0, 0xbfb8aa3b, v0
	v_fma_f32 v5, v5, v8, v77
	v_exp_f32_e32 v0, v0
	v_mul_f32_e32 v5, 0xbfb8aa3b, v5
	v_exp_f32_e32 v5, v5
	v_fma_f32 v4, v4, v8, v76
	v_mul_f32_e32 v4, 0xbfb8aa3b, v4
	v_exp_f32_e32 v4, v4
	v_add_f32_e32 v0, 1.0, v0
	v_lshlrev_b32_e32 v10, 16, v21
	v_and_b32_e32 v11, 0xffff0000, v21
	v_lshlrev_b32_e32 v20, 16, v22
	v_and_b32_e32 v21, 0xffff0000, v22
	v_rcp_f32_e32 v22, v0
	v_add_f32_e32 v0, 1.0, v5
	v_rcp_f32_e32 v5, v0
	v_fma_f32 v0, -v65, v9, v1
	v_fma_f32 v0, v0, v8, v69
	v_add_f32_e32 v4, 1.0, v4
	v_mul_f32_e32 v0, 0xbfb8aa3b, v0
	v_rcp_f32_e32 v4, v4
	s_waitcnt vmcnt(1)
	v_lshlrev_b32_e32 v24, 16, v16
	v_and_b32_e32 v25, 0xffff0000, v16
	v_exp_f32_e32 v16, v0
	v_sub_f32_e32 v13, v13, v9
	v_sub_f32_e32 v12, v12, v9
	v_fma_f32 v2, -v66, v9, v2
	v_pk_mul_f32 v[12:13], v[12:13], v[8:9] op_sel_hi:[1,0]
	v_fma_f32 v2, v2, v8, v70
	v_fma_f32 v7, -v75, v9, v7
	v_pk_fma_f32 v[0:1], v[88:89], v[12:13], v[92:93]
	v_mul_f32_e32 v2, 0xbfb8aa3b, v2
	v_fmac_f32_e32 v79, v7, v8
	v_pk_fma_f32 v[0:1], v[4:5], v[24:25], v[0:1]
	v_add_f32_e32 v4, 1.0, v16
	v_exp_f32_e32 v2, v2
	v_mul_f32_e32 v7, 0xbfb8aa3b, v79
	v_lshlrev_b32_e32 v14, 16, v23
	v_and_b32_e32 v15, 0xffff0000, v23
	v_rcp_f32_e32 v23, v4
	v_fma_f32 v6, -v74, v9, v6
	v_exp_f32_e32 v7, v7
	v_sub_f32_e32 v15, v15, v9
	v_sub_f32_e32 v14, v14, v9
	v_sub_f32_e32 v21, v21, v9
	v_sub_f32_e32 v20, v20, v9
	v_fma_f32 v6, v6, v8, v78
	v_pk_mul_f32 v[20:21], v[20:21], v[8:9] op_sel_hi:[1,0]
	v_pk_mul_f32 v[14:15], v[14:15], v[8:9] op_sel_hi:[1,0]
	v_mul_f32_e32 v6, 0xbfb8aa3b, v6
	v_lshlrev_b32_e32 v4, 16, v18
	v_and_b32_e32 v5, 0xffff0000, v18
	v_exp_f32_e32 v6, v6
	v_pk_fma_f32 v[12:13], v[82:83], v[14:15], v[86:87]
	v_pk_fma_f32 v[14:15], v[80:81], v[20:21], v[84:85]
	v_add_f32_e32 v2, 1.0, v2
	v_pk_fma_f32 v[4:5], v[22:23], v[4:5], v[14:15]
	v_rcp_f32_e32 v14, v2
	v_add_f32_e32 v2, 1.0, v7
	v_rcp_f32_e32 v7, v2
	v_fma_f32 v2, -v67, v9, v3
	v_fmac_f32_e32 v71, v2, v8
	v_sub_f32_e32 v11, v11, v9
	v_sub_f32_e32 v10, v10, v9
	v_add_f32_e32 v6, 1.0, v6
	v_mul_f32_e32 v2, 0xbfb8aa3b, v71
	v_pk_mul_f32 v[10:11], v[10:11], v[8:9] op_sel_hi:[1,0]
	v_rcp_f32_e32 v6, v6
	v_exp_f32_e32 v8, v2
	v_pk_fma_f32 v[10:11], v[90:91], v[10:11], v[94:95]
	v_lshlrev_b32_e32 v2, 16, v17
	v_and_b32_e32 v3, 0xffff0000, v17
	v_pk_fma_f32 v[2:3], v[6:7], v[2:3], v[10:11]
	v_add_f32_e32 v6, 1.0, v8
	v_rcp_f32_e32 v15, v6
	v_lshlrev_b32_e32 v6, 16, v19
	v_and_b32_e32 v7, 0xffff0000, v19
	s_and_b64 vcc, exec, s[46:47]
	v_pk_fma_f32 v[6:7], v[14:15], v[6:7], v[12:13]
	s_cbranch_vccnz .LBB0_1909
	v_cndmask_b32_e64 v11, v3, v7, s[40:41]
	v_cndmask_b32_e64 v10, v2, v6, s[40:41]
	v_cndmask_b32_e64 v9, v1, v5, s[40:41]
	v_cndmask_b32_e64 v8, v0, v4, s[40:41]
	s_nop 1
	v_mov_b32_dpp v8, v8 row_ror:8 row_mask:0xf bank_mask:0xf
	s_nop 1
	v_mov_b32_dpp v9, v9 row_ror:8 row_mask:0xf bank_mask:0xf
	s_nop 1
	v_mov_b32_dpp v10, v10 row_ror:8 row_mask:0xf bank_mask:0xf
	s_nop 1
	v_mov_b32_dpp v11, v11 row_ror:8 row_mask:0xf bank_mask:0xf
	s_and_saveexec_b64 s[12:13], s[42:43]
	s_xor_b64 s[12:13], exec, s[12:13]
	v_mov_b64_e32 v[14:15], v[6:7]
	v_lshl_add_u64 v[16:17], v[128:129], 0, v[118:119]
	v_mov_b64_e32 v[12:13], v[4:5]
	s_andn2_saveexec_b64 s[12:13], s[12:13]
	v_or_b32_e32 v12, 56, v152
	v_ashrrev_i32_e32 v13, 31, v12
	v_lshlrev_b64 v[12:13], 11, v[12:13]
	v_lshl_add_u64 v[16:17], v[12:13], 0, v[114:115]
	v_mov_b64_e32 v[14:15], v[10:11]
	v_mov_b64_e32 v[12:13], v[8:9]
	v_mov_b64_e32 v[10:11], v[2:3]
	v_mov_b64_e32 v[8:9], v[0:1]
	s_or_b64 exec, exec, s[12:13]
	v_add_u32_e32 v20, 0xa8, v178
	v_ashrrev_i32_e32 v21, 31, v20
	v_lshlrev_b64 v[20:21], 11, v[20:21]
	v_lshl_add_u64 v[18:19], v[128:129], 0, v[114:115]
	v_lshl_add_u64 v[20:21], v[20:21], 0, v[118:119]
	v_cndmask_b32_e64 v19, v21, v19, s[40:41]
	v_cndmask_b32_e64 v18, v20, v18, s[40:41]
	v_lshl_add_u64 v[18:19], v[18:19], 2, s[4:5]
	global_store_dwordx4 v[18:19], v[8:11], off nt
	s_nop 1
	v_lshl_add_u64 v[8:9], v[16:17], 2, s[4:5]
	global_store_dwordx4 v[8:9], v[12:15], off nt
	s_branch .LBB0_1891
